# prep: modulation GEMV inner loop fully unrolled with all 64 weight loads issued up front (counted vmcnt), on top of v20
# baseline (speedup 1.0000x reference)
.LBB0_39:
	s_mov_b32 s4, 0x2aaaaaab
	v_mul_hi_i32 v2, v17, s4
	v_lshrrev_b32_e32 v3, 31, v2
	v_ashrrev_i32_e32 v2, 4, v2
	v_add_u32_e32 v26, v2, v3
	v_lshlrev_b32_e32 v14, 6, v26
	v_or_b32_e32 v2, v14, v1
	v_ashrrev_i32_e32 v3, 31, v2
	v_lshlrev_b64 v[4:5], 2, v[2:3]
	v_add_u32_e32 v6, v19, v14
	v_add_u32_e32 v8, v20, v14
	v_add_u32_e32 v10, v21, v14
	v_add_u32_e32 v12, v22, v14
	v_lshl_add_u64 v[2:3], s[22:23], 0, v[4:5]
	v_ashrrev_i32_e32 v7, 31, v6
	v_ashrrev_i32_e32 v9, 31, v8
	v_ashrrev_i32_e32 v11, 31, v10
	v_ashrrev_i32_e32 v13, 31, v12
	v_lshl_add_u64 v[6:7], v[6:7], 2, s[22:23]
	v_lshl_add_u64 v[8:9], v[8:9], 2, s[22:23]
	v_lshl_add_u64 v[10:11], v[10:11], 2, s[22:23]
	v_lshl_add_u64 v[12:13], v[12:13], 2, s[22:23]
	flat_load_dword v15, v[2:3]
	flat_load_dword v16, v[6:7]
	flat_load_dword v18, v[8:9]
	flat_load_dword v30, v[10:11]
	flat_load_dword v31, v[12:13]
	v_add_u32_e32 v6, v23, v14
	v_add_u32_e32 v8, v24, v14
	v_add_u32_e32 v10, v25, v14
	v_ashrrev_i32_e32 v7, 31, v6
	v_ashrrev_i32_e32 v9, 31, v8
	v_ashrrev_i32_e32 v11, 31, v10
	v_lshl_add_u64 v[6:7], v[6:7], 2, s[22:23]
	v_lshl_add_u64 v[8:9], v[8:9], 2, s[22:23]
	v_lshl_add_u64 v[10:11], v[10:11], 2, s[22:23]
	v_lshl_add_u64 v[4:5], s[16:17], 0, v[4:5]
	flat_load_dword v3, v[6:7]
	flat_load_dword v12, v[8:9]
	flat_load_dword v13, v[10:11]
	flat_load_dword v34, v[4:5]
	s_movk_i32 s4, 0x60
	v_mul_lo_u32 v2, v26, s4
	v_sub_u32_e32 v2, v17, v2
	v_lshl_or_b32 v2, v2, 6, v1
	s_mov_b32 s96, 0
	s_waitcnt vmcnt(0) lgkmcnt(0)
	v_mul_f32_e32 v4, 0xbfb8aa3b, v15
	v_mul_f32_e32 v5, 0xbfb8aa3b, v16
	v_exp_f32_e32 v4, v4
	v_mul_f32_e32 v6, 0xbfb8aa3b, v18
	v_exp_f32_e32 v5, v5
	v_exp_f32_e32 v6, v6
	v_add_f32_e32 v4, 1.0, v4
	v_div_scale_f32 v9, s[4:5], v4, v4, v15
	v_add_f32_e32 v5, 1.0, v5
	v_mul_f32_e32 v7, 0xbfb8aa3b, v30
	v_add_f32_e32 v6, 1.0, v6
	v_div_scale_f32 v11, s[4:5], v5, v5, v16
	v_rcp_f32_e32 v35, v9
	v_exp_f32_e32 v7, v7
	v_div_scale_f32 v28, s[4:5], v6, v6, v18
	v_rcp_f32_e32 v36, v11
	v_rcp_f32_e32 v37, v28
	v_fma_f32 v39, -v9, v35, 1.0
	v_add_f32_e32 v7, 1.0, v7
	v_div_scale_f32 v10, vcc, v15, v4, v15
	v_fma_f32 v40, -v11, v36, 1.0
	v_fmac_f32_e32 v35, v39, v35
	v_div_scale_f32 v27, s[6:7], v16, v5, v16
	v_div_scale_f32 v32, s[4:5], v7, v7, v30
	v_fma_f32 v41, -v28, v37, 1.0
	v_fmac_f32_e32 v36, v40, v36
	v_mul_f32_e32 v39, v10, v35
	v_mul_f32_e32 v8, 0xbfb8aa3b, v31
	v_div_scale_f32 v29, s[8:9], v18, v6, v18
	v_rcp_f32_e32 v38, v32
	v_fmac_f32_e32 v37, v41, v37
	v_mul_f32_e32 v40, v27, v36
	v_fma_f32 v43, -v9, v39, v10
	v_exp_f32_e32 v8, v8
	v_mul_f32_e32 v41, v29, v37
	v_fma_f32 v44, -v11, v40, v27
	v_fmac_f32_e32 v39, v43, v35
	v_fma_f32 v45, -v28, v41, v29
	v_fmac_f32_e32 v40, v44, v36
	v_fma_f32 v9, -v9, v39, v10
	v_fmac_f32_e32 v41, v45, v37
	v_fma_f32 v10, -v11, v40, v27
	v_div_fmas_f32 v9, v9, v35, v39
	s_mov_b64 vcc, s[6:7]
	v_fma_f32 v42, -v32, v38, 1.0
	v_fma_f32 v11, -v28, v41, v29
	v_div_fixup_f32 v27, v9, v4, v15
	v_div_fmas_f32 v4, v10, v36, v40
	s_mov_b64 vcc, s[8:9]
	v_div_scale_f32 v33, s[10:11], v30, v7, v30
	v_fmac_f32_e32 v38, v42, v38
	v_div_fixup_f32 v28, v4, v5, v16
	v_div_fmas_f32 v4, v11, v37, v41
	v_add_f32_e32 v5, 1.0, v8
	v_mul_f32_e32 v42, v33, v38
	v_div_fixup_f32 v29, v4, v6, v18
	v_div_scale_f32 v6, s[4:5], v5, v5, v31
	v_fma_f32 v46, -v32, v42, v33
	v_rcp_f32_e32 v8, v6
	v_fmac_f32_e32 v42, v46, v38
	v_fma_f32 v4, -v32, v42, v33
	s_mov_b64 vcc, s[10:11]
	v_div_fmas_f32 v4, v4, v38, v42
	v_div_fixup_f32 v30, v4, v7, v30
	v_fma_f32 v4, -v6, v8, 1.0
	v_mul_f32_e32 v9, 0xbfb8aa3b, v3
	v_fmac_f32_e32 v8, v4, v8
	v_div_scale_f32 v4, vcc, v31, v5, v31
	v_exp_f32_e32 v9, v9
	v_mul_f32_e32 v7, v4, v8
	v_fma_f32 v10, -v6, v7, v4
	v_fmac_f32_e32 v7, v10, v8
	v_fma_f32 v4, -v6, v7, v4
	v_add_f32_e32 v6, 1.0, v9
	v_div_scale_f32 v9, s[4:5], v6, v6, v3
	v_rcp_f32_e32 v10, v9
	v_div_fmas_f32 v4, v4, v8, v7
	v_mul_f32_e32 v7, 0xbfb8aa3b, v12
	v_exp_f32_e32 v7, v7
	v_div_fixup_f32 v31, v4, v5, v31
	v_fma_f32 v4, -v9, v10, 1.0
	v_fmac_f32_e32 v10, v4, v10
	v_div_scale_f32 v4, vcc, v3, v6, v3
	v_mul_f32_e32 v5, v4, v10
	v_fma_f32 v8, -v9, v5, v4
	v_add_f32_e32 v7, 1.0, v7
	v_fmac_f32_e32 v5, v8, v10
	v_div_scale_f32 v8, s[4:5], v7, v7, v12
	v_fma_f32 v4, -v9, v5, v4
	v_rcp_f32_e32 v9, v8
	v_div_fmas_f32 v4, v4, v10, v5
	v_mul_f32_e32 v5, 0xbfb8aa3b, v13
	v_exp_f32_e32 v5, v5
	v_div_fixup_f32 v32, v4, v6, v3
	v_fma_f32 v3, -v8, v9, 1.0
	v_fmac_f32_e32 v9, v3, v9
	v_div_scale_f32 v3, vcc, v12, v7, v12
	v_mul_f32_e32 v4, v3, v9
	v_fma_f32 v6, -v8, v4, v3
	v_add_f32_e32 v5, 1.0, v5
	v_fmac_f32_e32 v4, v6, v9
	v_div_scale_f32 v6, s[4:5], v5, v5, v13
	v_fma_f32 v3, -v8, v4, v3
	v_rcp_f32_e32 v8, v6
	v_div_fmas_f32 v3, v3, v9, v4
	v_div_fixup_f32 v33, v3, v7, v12
	v_mul_f32_e32 v7, 0xbfb8aa3b, v34
	v_fma_f32 v3, -v6, v8, 1.0
	v_fmac_f32_e32 v8, v3, v8
	v_div_scale_f32 v3, vcc, v13, v5, v13
	v_exp_f32_e32 v7, v7
	v_mul_f32_e32 v4, v3, v8
	v_fma_f32 v9, -v6, v4, v3
	v_fmac_f32_e32 v4, v9, v8
	v_fma_f32 v3, -v6, v4, v3
	v_add_f32_e32 v6, 1.0, v7
	v_div_scale_f32 v7, s[4:5], v6, v6, v34
	v_rcp_f32_e32 v9, v7
	v_div_fmas_f32 v3, v3, v8, v4
	v_div_fixup_f32 v35, v3, v5, v13
	v_mov_b32_e32 v8, 0
	v_fma_f32 v3, -v7, v9, 1.0
	v_fmac_f32_e32 v9, v3, v9
	v_div_scale_f32 v3, vcc, v34, v6, v34
	v_mul_f32_e32 v4, v3, v9
	v_fma_f32 v5, -v7, v4, v3
	v_fmac_f32_e32 v4, v5, v9
	v_fma_f32 v3, -v7, v4, v3
	v_div_fmas_f32 v3, v3, v9, v4
	v_div_fixup_f32 v36, v3, v6, v34
	v_ashrrev_i32_e32 v3, 31, v2
	v_lshlrev_b64 v[4:5], 2, v[2:3]
	v_mad_i64_i32 v[4:5], s[4:5], v14, s39, v[4:5]
	v_mov_b32_e32 v34, 0
	v_lshl_add_u64 v[6:7], s[18:19], 0, v[4:5]
	v_mov_b32_e32 v4, 0
	v_mov_b32_e32 v5, v34
	v_mov_b32_e32 v9, v34
	v_mov_b32_e32 v10, 0
	v_mov_b32_e32 v11, v34
	v_mov_b32_e32 v12, 0
	v_mov_b32_e32 v13, v34
	s_mov_b32 s100, 0x6000
	s_mov_b32 s101, 0
	s_mov_b32 s98, 0xfffd6000
	s_mov_b32 s99, -1
	v_lshl_add_u64 v[124:125], v[6:7], 0, s[98:99]
	global_load_dword v60, v[124:125], off
	v_lshl_add_u64 v[124:125], v[124:125], 0, s[100:101]
	global_load_dword v61, v[124:125], off
	v_lshl_add_u64 v[124:125], v[124:125], 0, s[100:101]
	global_load_dword v62, v[124:125], off
	v_lshl_add_u64 v[124:125], v[124:125], 0, s[100:101]
	global_load_dword v63, v[124:125], off
	v_lshl_add_u64 v[124:125], v[124:125], 0, s[100:101]
	global_load_dword v64, v[124:125], off
	v_lshl_add_u64 v[124:125], v[124:125], 0, s[100:101]
	global_load_dword v65, v[124:125], off
	v_lshl_add_u64 v[124:125], v[124:125], 0, s[100:101]
	global_load_dword v66, v[124:125], off
	v_lshl_add_u64 v[124:125], v[124:125], 0, s[100:101]
	global_load_dword v67, v[124:125], off
	v_lshl_add_u64 v[124:125], v[124:125], 0, s[100:101]
	global_load_dword v68, v[124:125], off
	v_lshl_add_u64 v[124:125], v[124:125], 0, s[100:101]
	global_load_dword v69, v[124:125], off
	v_lshl_add_u64 v[124:125], v[124:125], 0, s[100:101]
	global_load_dword v70, v[124:125], off
	v_lshl_add_u64 v[124:125], v[124:125], 0, s[100:101]
	global_load_dword v71, v[124:125], off
	v_lshl_add_u64 v[124:125], v[124:125], 0, s[100:101]
	global_load_dword v72, v[124:125], off
	v_lshl_add_u64 v[124:125], v[124:125], 0, s[100:101]
	global_load_dword v73, v[124:125], off
	v_lshl_add_u64 v[124:125], v[124:125], 0, s[100:101]
	global_load_dword v74, v[124:125], off
	v_lshl_add_u64 v[124:125], v[124:125], 0, s[100:101]
	global_load_dword v75, v[124:125], off
	v_lshl_add_u64 v[124:125], v[124:125], 0, s[100:101]
	global_load_dword v76, v[124:125], off
	v_lshl_add_u64 v[124:125], v[124:125], 0, s[100:101]
	global_load_dword v77, v[124:125], off
	v_lshl_add_u64 v[124:125], v[124:125], 0, s[100:101]
	global_load_dword v78, v[124:125], off
	v_lshl_add_u64 v[124:125], v[124:125], 0, s[100:101]
	global_load_dword v79, v[124:125], off
	v_lshl_add_u64 v[124:125], v[124:125], 0, s[100:101]
	global_load_dword v80, v[124:125], off
	v_lshl_add_u64 v[124:125], v[124:125], 0, s[100:101]
	global_load_dword v81, v[124:125], off
	v_lshl_add_u64 v[124:125], v[124:125], 0, s[100:101]
	global_load_dword v82, v[124:125], off
	v_lshl_add_u64 v[124:125], v[124:125], 0, s[100:101]
	global_load_dword v83, v[124:125], off
	v_lshl_add_u64 v[124:125], v[124:125], 0, s[100:101]
	global_load_dword v84, v[124:125], off
	v_lshl_add_u64 v[124:125], v[124:125], 0, s[100:101]
	global_load_dword v85, v[124:125], off
	v_lshl_add_u64 v[124:125], v[124:125], 0, s[100:101]
	global_load_dword v86, v[124:125], off
	v_lshl_add_u64 v[124:125], v[124:125], 0, s[100:101]
	global_load_dword v87, v[124:125], off
	v_lshl_add_u64 v[124:125], v[124:125], 0, s[100:101]
	global_load_dword v88, v[124:125], off
	v_lshl_add_u64 v[124:125], v[124:125], 0, s[100:101]
	global_load_dword v89, v[124:125], off
	v_lshl_add_u64 v[124:125], v[124:125], 0, s[100:101]
	global_load_dword v90, v[124:125], off
	v_lshl_add_u64 v[124:125], v[124:125], 0, s[100:101]
	global_load_dword v91, v[124:125], off
	v_lshl_add_u64 v[124:125], v[124:125], 0, s[100:101]
	global_load_dword v92, v[124:125], off
	v_lshl_add_u64 v[124:125], v[124:125], 0, s[100:101]
	global_load_dword v93, v[124:125], off
	v_lshl_add_u64 v[124:125], v[124:125], 0, s[100:101]
	global_load_dword v94, v[124:125], off
	v_lshl_add_u64 v[124:125], v[124:125], 0, s[100:101]
	global_load_dword v95, v[124:125], off
	v_lshl_add_u64 v[124:125], v[124:125], 0, s[100:101]
	global_load_dword v96, v[124:125], off
	v_lshl_add_u64 v[124:125], v[124:125], 0, s[100:101]
	global_load_dword v97, v[124:125], off
	v_lshl_add_u64 v[124:125], v[124:125], 0, s[100:101]
	global_load_dword v98, v[124:125], off
	v_lshl_add_u64 v[124:125], v[124:125], 0, s[100:101]
	global_load_dword v99, v[124:125], off
	v_lshl_add_u64 v[124:125], v[124:125], 0, s[100:101]
	global_load_dword v100, v[124:125], off
	v_lshl_add_u64 v[124:125], v[124:125], 0, s[100:101]
	global_load_dword v101, v[124:125], off
	v_lshl_add_u64 v[124:125], v[124:125], 0, s[100:101]
	global_load_dword v102, v[124:125], off
	v_lshl_add_u64 v[124:125], v[124:125], 0, s[100:101]
	global_load_dword v103, v[124:125], off
	v_lshl_add_u64 v[124:125], v[124:125], 0, s[100:101]
	global_load_dword v104, v[124:125], off
	v_lshl_add_u64 v[124:125], v[124:125], 0, s[100:101]
	global_load_dword v105, v[124:125], off
	v_lshl_add_u64 v[124:125], v[124:125], 0, s[100:101]
	global_load_dword v106, v[124:125], off
	v_lshl_add_u64 v[124:125], v[124:125], 0, s[100:101]
	global_load_dword v107, v[124:125], off
	v_lshl_add_u64 v[124:125], v[124:125], 0, s[100:101]
	global_load_dword v108, v[124:125], off
	v_lshl_add_u64 v[124:125], v[124:125], 0, s[100:101]
	global_load_dword v109, v[124:125], off
	v_lshl_add_u64 v[124:125], v[124:125], 0, s[100:101]
	global_load_dword v110, v[124:125], off
	v_lshl_add_u64 v[124:125], v[124:125], 0, s[100:101]
	global_load_dword v111, v[124:125], off
	v_lshl_add_u64 v[124:125], v[124:125], 0, s[100:101]
	global_load_dword v112, v[124:125], off
	v_lshl_add_u64 v[124:125], v[124:125], 0, s[100:101]
	global_load_dword v113, v[124:125], off
	v_lshl_add_u64 v[124:125], v[124:125], 0, s[100:101]
	global_load_dword v114, v[124:125], off
	v_lshl_add_u64 v[124:125], v[124:125], 0, s[100:101]
	global_load_dword v115, v[124:125], off
	v_lshl_add_u64 v[124:125], v[124:125], 0, s[100:101]
	global_load_dword v116, v[124:125], off
	v_lshl_add_u64 v[124:125], v[124:125], 0, s[100:101]
	global_load_dword v117, v[124:125], off
	v_lshl_add_u64 v[124:125], v[124:125], 0, s[100:101]
	global_load_dword v118, v[124:125], off
	v_lshl_add_u64 v[124:125], v[124:125], 0, s[100:101]
	global_load_dword v119, v[124:125], off
	v_lshl_add_u64 v[124:125], v[124:125], 0, s[100:101]
	global_load_dword v120, v[124:125], off
	v_lshl_add_u64 v[124:125], v[124:125], 0, s[100:101]
	global_load_dword v121, v[124:125], off
	v_lshl_add_u64 v[124:125], v[124:125], 0, s[100:101]
	global_load_dword v122, v[124:125], off
	v_lshl_add_u64 v[124:125], v[124:125], 0, s[100:101]
	global_load_dword v123, v[124:125], off
	s_mov_b32 s6, 0xfffdc000
	v_add_co_u32_e64 v38, s[6:7], s6, v6
	v_add_co_u32_e32 v14, vcc, 0xfffd6000, v6
	s_nop 0
	v_addc_co_u32_e64 v39, s[6:7], -1, v7, s[6:7]
	s_mov_b32 s6, 0xfffe2000
	s_nop 0
	v_add_co_u32_e64 v40, s[6:7], s6, v6
	s_waitcnt vmcnt(56)
	v_mov_b32_e32 v16, v67
	s_nop 0
	v_addc_co_u32_e64 v41, s[6:7], -1, v7, s[6:7]
	s_mov_b32 s6, 0xfffe8000
	s_nop 0
	v_add_co_u32_e64 v42, s[6:7], s6, v6
	v_addc_co_u32_e32 v15, vcc, -1, v7, vcc
	s_nop 0
	v_addc_co_u32_e64 v43, s[6:7], -1, v7, s[6:7]
	s_mov_b32 s6, 0xfffee000
	s_nop 0
	v_add_co_u32_e64 v44, s[6:7], s6, v6
	v_readlane_b32 s9, v27, s96
	s_nop 0
	v_addc_co_u32_e64 v45, s[6:7], -1, v7, s[6:7]
	s_mov_b32 s6, 0xffff4000
	s_nop 0
	v_add_co_u32_e64 v46, s[6:7], s6, v6
	v_readlane_b32 s11, v28, s96
	s_nop 0
	v_addc_co_u32_e64 v47, s[6:7], -1, v7, s[6:7]
	s_movk_i32 s6, 0xa000
	s_nop 0
	v_add_co_u32_e64 v48, s[6:7], s6, v6
	v_readlane_b32 s26, v29, s96
	s_nop 0
	v_addc_co_u32_e64 v49, s[6:7], -1, v7, s[6:7]
	v_mov_b32_e32 v38, v61
	s_nop 0
	v_mov_b32_e32 v40, v62
	s_nop 0
	v_mov_b32_e32 v42, v63
	s_nop 0
	v_mov_b32_e32 v44, v64
	s_nop 0
	v_mov_b32_e32 v46, v65
	s_nop 0
	v_mov_b32_e32 v18, v66
	s_nop 0
	v_mov_b32_e32 v14, v60
	v_readlane_b32 s97, v30, s96
	v_readlane_b32 s27, v31, s96
	v_readlane_b32 s10, v32, s96
	v_readlane_b32 s8, v33, s96
	v_readlane_b32 s29, v35, s96
	v_readlane_b32 s28, v36, s96
	s_add_i32 s36, s96, 1
	s_add_i32 s52, s96, 2
	v_readlane_b32 s7, v27, s36
	v_readlane_b32 s31, v28, s36
	v_readlane_b32 s34, v29, s36
	v_readlane_b32 s94, v30, s36
	v_readlane_b32 s35, v31, s36
	v_readlane_b32 s30, v32, s36
	v_readlane_b32 s6, v33, s36
	v_readlane_b32 s47, v35, s36
	v_readlane_b32 s46, v36, s36
	s_add_i32 s33, s96, 3
	v_readlane_b32 s37, v27, s52
	v_readlane_b32 s49, v28, s52
	v_readlane_b32 s50, v29, s52
	v_readlane_b32 s44, v30, s52
	v_readlane_b32 s51, v31, s52
	v_readlane_b32 s48, v32, s52
	v_readlane_b32 s36, v33, s52
	v_readlane_b32 s53, v35, s52
	v_readlane_b32 s52, v36, s52
	s_add_i32 s68, s96, 4
	v_readlane_b32 s55, v27, s33
	v_readlane_b32 s57, v28, s33
	v_readlane_b32 s58, v29, s33
	v_readlane_b32 s45, v30, s33
	v_readlane_b32 s59, v31, s33
	v_readlane_b32 s56, v32, s33
	v_readlane_b32 s54, v33, s33
	v_readlane_b32 s63, v35, s33
	v_readlane_b32 s62, v36, s33
	s_add_i32 s4, s96, 5
	v_readlane_b32 s61, v27, s68
	v_readlane_b32 s65, v28, s68
	v_readlane_b32 s66, v29, s68
	v_readlane_b32 s33, v30, s68
	v_readlane_b32 s67, v31, s68
	v_readlane_b32 s64, v32, s68
	v_readlane_b32 s60, v33, s68
	v_readlane_b32 s71, v35, s68
	v_readlane_b32 s70, v36, s68
	s_add_i32 s5, s96, 6
	v_readlane_b32 s69, v27, s4
	v_readlane_b32 s73, v28, s4
	v_readlane_b32 s74, v29, s4
	v_readlane_b32 vcc_lo, v30, s4
	v_readlane_b32 s75, v31, s4
	v_readlane_b32 s72, v32, s4
	v_readlane_b32 s68, v33, s4
	v_readlane_b32 s79, v35, s4
	v_readlane_b32 s78, v36, s4
	s_add_i32 s40, s96, 7
	v_readlane_b32 s77, v27, s5
	v_readlane_b32 s81, v28, s5
	v_readlane_b32 s82, v29, s5
	v_readlane_b32 vcc_hi, v30, s5
	v_readlane_b32 s83, v31, s5
	v_readlane_b32 s80, v32, s5
	v_readlane_b32 s76, v33, s5
	v_readlane_b32 s87, v35, s5
	v_readlane_b32 s86, v36, s5
	s_add_i32 s96, s96, 8
	v_readlane_b32 s85, v27, s40
	v_readlane_b32 s89, v28, s40
	v_readlane_b32 s90, v29, s40
	v_readlane_b32 s91, v31, s40
	v_readlane_b32 s88, v32, s40
	v_readlane_b32 s84, v33, s40
	v_readlane_b32 s93, v35, s40
	v_readlane_b32 s92, v36, s40
	v_readlane_b32 s4, v30, s40
	s_mov_b64 s[40:41], 0x30000
	s_cmp_eq_u32 s96, 64
	s_nop 0
	v_fmac_f32_e32 v34, s97, v14
	v_pk_fma_f32 v[12:13], v[14:15], s[26:27], v[12:13] op_sel_hi:[0,1,1]
	v_pk_fma_f32 v[10:11], v[14:15], s[10:11], v[10:11] op_sel_hi:[0,1,1]
	v_pk_fma_f32 v[8:9], v[14:15], s[8:9], v[8:9] op_sel_hi:[0,1,1]
	v_pk_fma_f32 v[4:5], v[14:15], s[28:29], v[4:5] op_sel_hi:[0,1,1]
	v_fmac_f32_e32 v34, s94, v38
	v_pk_fma_f32 v[12:13], v[38:39], s[34:35], v[12:13] op_sel_hi:[0,1,1]
	v_pk_fma_f32 v[10:11], v[38:39], s[30:31], v[10:11] op_sel_hi:[0,1,1]
	v_pk_fma_f32 v[8:9], v[38:39], s[6:7], v[8:9] op_sel_hi:[0,1,1]
	v_pk_fma_f32 v[4:5], v[38:39], s[46:47], v[4:5] op_sel_hi:[0,1,1]
	v_fmac_f32_e32 v34, s44, v40
	v_pk_fma_f32 v[12:13], v[40:41], s[50:51], v[12:13] op_sel_hi:[0,1,1]
	v_pk_fma_f32 v[10:11], v[40:41], s[48:49], v[10:11] op_sel_hi:[0,1,1]
	v_pk_fma_f32 v[8:9], v[40:41], s[36:37], v[8:9] op_sel_hi:[0,1,1]
	v_pk_fma_f32 v[4:5], v[40:41], s[52:53], v[4:5] op_sel_hi:[0,1,1]
	v_fmac_f32_e32 v34, s45, v42
	v_pk_fma_f32 v[12:13], v[42:43], s[58:59], v[12:13] op_sel_hi:[0,1,1]
	v_pk_fma_f32 v[10:11], v[42:43], s[56:57], v[10:11] op_sel_hi:[0,1,1]
	v_pk_fma_f32 v[8:9], v[42:43], s[54:55], v[8:9] op_sel_hi:[0,1,1]
	v_pk_fma_f32 v[4:5], v[42:43], s[62:63], v[4:5] op_sel_hi:[0,1,1]
	v_fmac_f32_e32 v34, s33, v44
	v_pk_fma_f32 v[12:13], v[44:45], s[66:67], v[12:13] op_sel_hi:[0,1,1]
	v_pk_fma_f32 v[10:11], v[44:45], s[64:65], v[10:11] op_sel_hi:[0,1,1]
	v_pk_fma_f32 v[8:9], v[44:45], s[60:61], v[8:9] op_sel_hi:[0,1,1]
	v_pk_fma_f32 v[4:5], v[44:45], s[70:71], v[4:5] op_sel_hi:[0,1,1]
	v_fmac_f32_e32 v34, vcc_lo, v46
	v_pk_fma_f32 v[12:13], v[46:47], s[74:75], v[12:13] op_sel_hi:[0,1,1]
	v_pk_fma_f32 v[10:11], v[46:47], s[72:73], v[10:11] op_sel_hi:[0,1,1]
	v_pk_fma_f32 v[8:9], v[46:47], s[68:69], v[8:9] op_sel_hi:[0,1,1]
	v_pk_fma_f32 v[4:5], v[46:47], s[78:79], v[4:5] op_sel_hi:[0,1,1]
	v_fmac_f32_e32 v34, vcc_hi, v18
	v_pk_fma_f32 v[12:13], v[18:19], s[82:83], v[12:13] op_sel_hi:[0,1,1]
	v_pk_fma_f32 v[10:11], v[18:19], s[80:81], v[10:11] op_sel_hi:[0,1,1]
	v_pk_fma_f32 v[8:9], v[18:19], s[76:77], v[8:9] op_sel_hi:[0,1,1]
	v_pk_fma_f32 v[4:5], v[18:19], s[86:87], v[4:5] op_sel_hi:[0,1,1]
	v_lshl_add_u64 v[6:7], v[6:7], 0, s[40:41]
	v_fmac_f32_e32 v34, s4, v16
	v_pk_fma_f32 v[12:13], v[16:17], s[90:91], v[12:13] op_sel_hi:[0,1,1]
	v_pk_fma_f32 v[10:11], v[16:17], s[88:89], v[10:11] op_sel_hi:[0,1,1]
	v_pk_fma_f32 v[8:9], v[16:17], s[84:85], v[8:9] op_sel_hi:[0,1,1]
	v_pk_fma_f32 v[4:5], v[16:17], s[92:93], v[4:5] op_sel_hi:[0,1,1]
	s_mov_b32 s6, 0xfffdc000
	v_add_co_u32_e64 v38, s[6:7], s6, v6
	v_add_co_u32_e32 v14, vcc, 0xfffd6000, v6
	s_nop 0
	v_addc_co_u32_e64 v39, s[6:7], -1, v7, s[6:7]
	s_mov_b32 s6, 0xfffe2000
	s_nop 0
	v_add_co_u32_e64 v40, s[6:7], s6, v6
	s_waitcnt vmcnt(48)
	v_mov_b32_e32 v16, v75
	s_nop 0
	v_addc_co_u32_e64 v41, s[6:7], -1, v7, s[6:7]
	s_mov_b32 s6, 0xfffe8000
	s_nop 0
	v_add_co_u32_e64 v42, s[6:7], s6, v6
	v_addc_co_u32_e32 v15, vcc, -1, v7, vcc
	s_nop 0
	v_addc_co_u32_e64 v43, s[6:7], -1, v7, s[6:7]
	s_mov_b32 s6, 0xfffee000
	s_nop 0
	v_add_co_u32_e64 v44, s[6:7], s6, v6
	v_readlane_b32 s9, v27, s96
	s_nop 0
	v_addc_co_u32_e64 v45, s[6:7], -1, v7, s[6:7]
	s_mov_b32 s6, 0xffff4000
	s_nop 0
	v_add_co_u32_e64 v46, s[6:7], s6, v6
	v_readlane_b32 s11, v28, s96
	s_nop 0
	v_addc_co_u32_e64 v47, s[6:7], -1, v7, s[6:7]
	s_movk_i32 s6, 0xa000
	s_nop 0
	v_add_co_u32_e64 v48, s[6:7], s6, v6
	v_readlane_b32 s26, v29, s96
	s_nop 0
	v_addc_co_u32_e64 v49, s[6:7], -1, v7, s[6:7]
	v_mov_b32_e32 v38, v69
	s_nop 0
	v_mov_b32_e32 v40, v70
	s_nop 0
	v_mov_b32_e32 v42, v71
	s_nop 0
	v_mov_b32_e32 v44, v72
	s_nop 0
	v_mov_b32_e32 v46, v73
	s_nop 0
	v_mov_b32_e32 v18, v74
	s_nop 0
	v_mov_b32_e32 v14, v68
	v_readlane_b32 s97, v30, s96
	v_readlane_b32 s27, v31, s96
	v_readlane_b32 s10, v32, s96
	v_readlane_b32 s8, v33, s96
	v_readlane_b32 s29, v35, s96
	v_readlane_b32 s28, v36, s96
	s_add_i32 s36, s96, 1
	s_add_i32 s52, s96, 2
	v_readlane_b32 s7, v27, s36
	v_readlane_b32 s31, v28, s36
	v_readlane_b32 s34, v29, s36
	v_readlane_b32 s94, v30, s36
	v_readlane_b32 s35, v31, s36
	v_readlane_b32 s30, v32, s36
	v_readlane_b32 s6, v33, s36
	v_readlane_b32 s47, v35, s36
	v_readlane_b32 s46, v36, s36
	s_add_i32 s33, s96, 3
	v_readlane_b32 s37, v27, s52
	v_readlane_b32 s49, v28, s52
	v_readlane_b32 s50, v29, s52
	v_readlane_b32 s44, v30, s52
	v_readlane_b32 s51, v31, s52
	v_readlane_b32 s48, v32, s52
	v_readlane_b32 s36, v33, s52
	v_readlane_b32 s53, v35, s52
	v_readlane_b32 s52, v36, s52
	s_add_i32 s68, s96, 4
	v_readlane_b32 s55, v27, s33
	v_readlane_b32 s57, v28, s33
	v_readlane_b32 s58, v29, s33
	v_readlane_b32 s45, v30, s33
	v_readlane_b32 s59, v31, s33
	v_readlane_b32 s56, v32, s33
	v_readlane_b32 s54, v33, s33
	v_readlane_b32 s63, v35, s33
	v_readlane_b32 s62, v36, s33
	s_add_i32 s4, s96, 5
	v_readlane_b32 s61, v27, s68
	v_readlane_b32 s65, v28, s68
	v_readlane_b32 s66, v29, s68
	v_readlane_b32 s33, v30, s68
	v_readlane_b32 s67, v31, s68
	v_readlane_b32 s64, v32, s68
	v_readlane_b32 s60, v33, s68
	v_readlane_b32 s71, v35, s68
	v_readlane_b32 s70, v36, s68
	s_add_i32 s5, s96, 6
	v_readlane_b32 s69, v27, s4
	v_readlane_b32 s73, v28, s4
	v_readlane_b32 s74, v29, s4
	v_readlane_b32 vcc_lo, v30, s4
	v_readlane_b32 s75, v31, s4
	v_readlane_b32 s72, v32, s4
	v_readlane_b32 s68, v33, s4
	v_readlane_b32 s79, v35, s4
	v_readlane_b32 s78, v36, s4
	s_add_i32 s40, s96, 7
	v_readlane_b32 s77, v27, s5
	v_readlane_b32 s81, v28, s5
	v_readlane_b32 s82, v29, s5
	v_readlane_b32 vcc_hi, v30, s5
	v_readlane_b32 s83, v31, s5
	v_readlane_b32 s80, v32, s5
	v_readlane_b32 s76, v33, s5
	v_readlane_b32 s87, v35, s5
	v_readlane_b32 s86, v36, s5
	s_add_i32 s96, s96, 8
	v_readlane_b32 s85, v27, s40
	v_readlane_b32 s89, v28, s40
	v_readlane_b32 s90, v29, s40
	v_readlane_b32 s91, v31, s40
	v_readlane_b32 s88, v32, s40
	v_readlane_b32 s84, v33, s40
	v_readlane_b32 s93, v35, s40
	v_readlane_b32 s92, v36, s40
	v_readlane_b32 s4, v30, s40
	s_mov_b64 s[40:41], 0x30000
	s_cmp_eq_u32 s96, 64
	s_nop 0
	v_fmac_f32_e32 v34, s97, v14
	v_pk_fma_f32 v[12:13], v[14:15], s[26:27], v[12:13] op_sel_hi:[0,1,1]
	v_pk_fma_f32 v[10:11], v[14:15], s[10:11], v[10:11] op_sel_hi:[0,1,1]
	v_pk_fma_f32 v[8:9], v[14:15], s[8:9], v[8:9] op_sel_hi:[0,1,1]
	v_pk_fma_f32 v[4:5], v[14:15], s[28:29], v[4:5] op_sel_hi:[0,1,1]
	v_fmac_f32_e32 v34, s94, v38
	v_pk_fma_f32 v[12:13], v[38:39], s[34:35], v[12:13] op_sel_hi:[0,1,1]
	v_pk_fma_f32 v[10:11], v[38:39], s[30:31], v[10:11] op_sel_hi:[0,1,1]
	v_pk_fma_f32 v[8:9], v[38:39], s[6:7], v[8:9] op_sel_hi:[0,1,1]
	v_pk_fma_f32 v[4:5], v[38:39], s[46:47], v[4:5] op_sel_hi:[0,1,1]
	v_fmac_f32_e32 v34, s44, v40
	v_pk_fma_f32 v[12:13], v[40:41], s[50:51], v[12:13] op_sel_hi:[0,1,1]
	v_pk_fma_f32 v[10:11], v[40:41], s[48:49], v[10:11] op_sel_hi:[0,1,1]
	v_pk_fma_f32 v[8:9], v[40:41], s[36:37], v[8:9] op_sel_hi:[0,1,1]
	v_pk_fma_f32 v[4:5], v[40:41], s[52:53], v[4:5] op_sel_hi:[0,1,1]
	v_fmac_f32_e32 v34, s45, v42
	v_pk_fma_f32 v[12:13], v[42:43], s[58:59], v[12:13] op_sel_hi:[0,1,1]
	v_pk_fma_f32 v[10:11], v[42:43], s[56:57], v[10:11] op_sel_hi:[0,1,1]
	v_pk_fma_f32 v[8:9], v[42:43], s[54:55], v[8:9] op_sel_hi:[0,1,1]
	v_pk_fma_f32 v[4:5], v[42:43], s[62:63], v[4:5] op_sel_hi:[0,1,1]
	v_fmac_f32_e32 v34, s33, v44
	v_pk_fma_f32 v[12:13], v[44:45], s[66:67], v[12:13] op_sel_hi:[0,1,1]
	v_pk_fma_f32 v[10:11], v[44:45], s[64:65], v[10:11] op_sel_hi:[0,1,1]
	v_pk_fma_f32 v[8:9], v[44:45], s[60:61], v[8:9] op_sel_hi:[0,1,1]
	v_pk_fma_f32 v[4:5], v[44:45], s[70:71], v[4:5] op_sel_hi:[0,1,1]
	v_fmac_f32_e32 v34, vcc_lo, v46
	v_pk_fma_f32 v[12:13], v[46:47], s[74:75], v[12:13] op_sel_hi:[0,1,1]
	v_pk_fma_f32 v[10:11], v[46:47], s[72:73], v[10:11] op_sel_hi:[0,1,1]
	v_pk_fma_f32 v[8:9], v[46:47], s[68:69], v[8:9] op_sel_hi:[0,1,1]
	v_pk_fma_f32 v[4:5], v[46:47], s[78:79], v[4:5] op_sel_hi:[0,1,1]
	v_fmac_f32_e32 v34, vcc_hi, v18
	v_pk_fma_f32 v[12:13], v[18:19], s[82:83], v[12:13] op_sel_hi:[0,1,1]
	v_pk_fma_f32 v[10:11], v[18:19], s[80:81], v[10:11] op_sel_hi:[0,1,1]
	v_pk_fma_f32 v[8:9], v[18:19], s[76:77], v[8:9] op_sel_hi:[0,1,1]
	v_pk_fma_f32 v[4:5], v[18:19], s[86:87], v[4:5] op_sel_hi:[0,1,1]
	v_lshl_add_u64 v[6:7], v[6:7], 0, s[40:41]
	v_fmac_f32_e32 v34, s4, v16
	v_pk_fma_f32 v[12:13], v[16:17], s[90:91], v[12:13] op_sel_hi:[0,1,1]
	v_pk_fma_f32 v[10:11], v[16:17], s[88:89], v[10:11] op_sel_hi:[0,1,1]
	v_pk_fma_f32 v[8:9], v[16:17], s[84:85], v[8:9] op_sel_hi:[0,1,1]
	v_pk_fma_f32 v[4:5], v[16:17], s[92:93], v[4:5] op_sel_hi:[0,1,1]
	s_mov_b32 s6, 0xfffdc000
	v_add_co_u32_e64 v38, s[6:7], s6, v6
	v_add_co_u32_e32 v14, vcc, 0xfffd6000, v6
	s_nop 0
	v_addc_co_u32_e64 v39, s[6:7], -1, v7, s[6:7]
	s_mov_b32 s6, 0xfffe2000
	s_nop 0
	v_add_co_u32_e64 v40, s[6:7], s6, v6
	s_waitcnt vmcnt(40)
	v_mov_b32_e32 v16, v83
	s_nop 0
	v_addc_co_u32_e64 v41, s[6:7], -1, v7, s[6:7]
	s_mov_b32 s6, 0xfffe8000
	s_nop 0
	v_add_co_u32_e64 v42, s[6:7], s6, v6
	v_addc_co_u32_e32 v15, vcc, -1, v7, vcc
	s_nop 0
	v_addc_co_u32_e64 v43, s[6:7], -1, v7, s[6:7]
	s_mov_b32 s6, 0xfffee000
	s_nop 0
	v_add_co_u32_e64 v44, s[6:7], s6, v6
	v_readlane_b32 s9, v27, s96
	s_nop 0
	v_addc_co_u32_e64 v45, s[6:7], -1, v7, s[6:7]
	s_mov_b32 s6, 0xffff4000
	s_nop 0
	v_add_co_u32_e64 v46, s[6:7], s6, v6
	v_readlane_b32 s11, v28, s96
	s_nop 0
	v_addc_co_u32_e64 v47, s[6:7], -1, v7, s[6:7]
	s_movk_i32 s6, 0xa000
	s_nop 0
	v_add_co_u32_e64 v48, s[6:7], s6, v6
	v_readlane_b32 s26, v29, s96
	s_nop 0
	v_addc_co_u32_e64 v49, s[6:7], -1, v7, s[6:7]
	v_mov_b32_e32 v38, v77
	s_nop 0
	v_mov_b32_e32 v40, v78
	s_nop 0
	v_mov_b32_e32 v42, v79
	s_nop 0
	v_mov_b32_e32 v44, v80
	s_nop 0
	v_mov_b32_e32 v46, v81
	s_nop 0
	v_mov_b32_e32 v18, v82
	s_nop 0
	v_mov_b32_e32 v14, v76
	v_readlane_b32 s97, v30, s96
	v_readlane_b32 s27, v31, s96
	v_readlane_b32 s10, v32, s96
	v_readlane_b32 s8, v33, s96
	v_readlane_b32 s29, v35, s96
	v_readlane_b32 s28, v36, s96
	s_add_i32 s36, s96, 1
	s_add_i32 s52, s96, 2
	v_readlane_b32 s7, v27, s36
	v_readlane_b32 s31, v28, s36
	v_readlane_b32 s34, v29, s36
	v_readlane_b32 s94, v30, s36
	v_readlane_b32 s35, v31, s36
	v_readlane_b32 s30, v32, s36
	v_readlane_b32 s6, v33, s36
	v_readlane_b32 s47, v35, s36
	v_readlane_b32 s46, v36, s36
	s_add_i32 s33, s96, 3
	v_readlane_b32 s37, v27, s52
	v_readlane_b32 s49, v28, s52
	v_readlane_b32 s50, v29, s52
	v_readlane_b32 s44, v30, s52
	v_readlane_b32 s51, v31, s52
	v_readlane_b32 s48, v32, s52
	v_readlane_b32 s36, v33, s52
	v_readlane_b32 s53, v35, s52
	v_readlane_b32 s52, v36, s52
	s_add_i32 s68, s96, 4
	v_readlane_b32 s55, v27, s33
	v_readlane_b32 s57, v28, s33
	v_readlane_b32 s58, v29, s33
	v_readlane_b32 s45, v30, s33
	v_readlane_b32 s59, v31, s33
	v_readlane_b32 s56, v32, s33
	v_readlane_b32 s54, v33, s33
	v_readlane_b32 s63, v35, s33
	v_readlane_b32 s62, v36, s33
	s_add_i32 s4, s96, 5
	v_readlane_b32 s61, v27, s68
	v_readlane_b32 s65, v28, s68
	v_readlane_b32 s66, v29, s68
	v_readlane_b32 s33, v30, s68
	v_readlane_b32 s67, v31, s68
	v_readlane_b32 s64, v32, s68
	v_readlane_b32 s60, v33, s68
	v_readlane_b32 s71, v35, s68
	v_readlane_b32 s70, v36, s68
	s_add_i32 s5, s96, 6
	v_readlane_b32 s69, v27, s4
	v_readlane_b32 s73, v28, s4
	v_readlane_b32 s74, v29, s4
	v_readlane_b32 vcc_lo, v30, s4
	v_readlane_b32 s75, v31, s4
	v_readlane_b32 s72, v32, s4
	v_readlane_b32 s68, v33, s4
	v_readlane_b32 s79, v35, s4
	v_readlane_b32 s78, v36, s4
	s_add_i32 s40, s96, 7
	v_readlane_b32 s77, v27, s5
	v_readlane_b32 s81, v28, s5
	v_readlane_b32 s82, v29, s5
	v_readlane_b32 vcc_hi, v30, s5
	v_readlane_b32 s83, v31, s5
	v_readlane_b32 s80, v32, s5
	v_readlane_b32 s76, v33, s5
	v_readlane_b32 s87, v35, s5
	v_readlane_b32 s86, v36, s5
	s_add_i32 s96, s96, 8
	v_readlane_b32 s85, v27, s40
	v_readlane_b32 s89, v28, s40
	v_readlane_b32 s90, v29, s40
	v_readlane_b32 s91, v31, s40
	v_readlane_b32 s88, v32, s40
	v_readlane_b32 s84, v33, s40
	v_readlane_b32 s93, v35, s40
	v_readlane_b32 s92, v36, s40
	v_readlane_b32 s4, v30, s40
	s_mov_b64 s[40:41], 0x30000
	s_cmp_eq_u32 s96, 64
	s_nop 0
	v_fmac_f32_e32 v34, s97, v14
	v_pk_fma_f32 v[12:13], v[14:15], s[26:27], v[12:13] op_sel_hi:[0,1,1]
	v_pk_fma_f32 v[10:11], v[14:15], s[10:11], v[10:11] op_sel_hi:[0,1,1]
	v_pk_fma_f32 v[8:9], v[14:15], s[8:9], v[8:9] op_sel_hi:[0,1,1]
	v_pk_fma_f32 v[4:5], v[14:15], s[28:29], v[4:5] op_sel_hi:[0,1,1]
	v_fmac_f32_e32 v34, s94, v38
	v_pk_fma_f32 v[12:13], v[38:39], s[34:35], v[12:13] op_sel_hi:[0,1,1]
	v_pk_fma_f32 v[10:11], v[38:39], s[30:31], v[10:11] op_sel_hi:[0,1,1]
	v_pk_fma_f32 v[8:9], v[38:39], s[6:7], v[8:9] op_sel_hi:[0,1,1]
	v_pk_fma_f32 v[4:5], v[38:39], s[46:47], v[4:5] op_sel_hi:[0,1,1]
	v_fmac_f32_e32 v34, s44, v40
	v_pk_fma_f32 v[12:13], v[40:41], s[50:51], v[12:13] op_sel_hi:[0,1,1]
	v_pk_fma_f32 v[10:11], v[40:41], s[48:49], v[10:11] op_sel_hi:[0,1,1]
	v_pk_fma_f32 v[8:9], v[40:41], s[36:37], v[8:9] op_sel_hi:[0,1,1]
	v_pk_fma_f32 v[4:5], v[40:41], s[52:53], v[4:5] op_sel_hi:[0,1,1]
	v_fmac_f32_e32 v34, s45, v42
	v_pk_fma_f32 v[12:13], v[42:43], s[58:59], v[12:13] op_sel_hi:[0,1,1]
	v_pk_fma_f32 v[10:11], v[42:43], s[56:57], v[10:11] op_sel_hi:[0,1,1]
	v_pk_fma_f32 v[8:9], v[42:43], s[54:55], v[8:9] op_sel_hi:[0,1,1]
	v_pk_fma_f32 v[4:5], v[42:43], s[62:63], v[4:5] op_sel_hi:[0,1,1]
	v_fmac_f32_e32 v34, s33, v44
	v_pk_fma_f32 v[12:13], v[44:45], s[66:67], v[12:13] op_sel_hi:[0,1,1]
	v_pk_fma_f32 v[10:11], v[44:45], s[64:65], v[10:11] op_sel_hi:[0,1,1]
	v_pk_fma_f32 v[8:9], v[44:45], s[60:61], v[8:9] op_sel_hi:[0,1,1]
	v_pk_fma_f32 v[4:5], v[44:45], s[70:71], v[4:5] op_sel_hi:[0,1,1]
	v_fmac_f32_e32 v34, vcc_lo, v46
	v_pk_fma_f32 v[12:13], v[46:47], s[74:75], v[12:13] op_sel_hi:[0,1,1]
	v_pk_fma_f32 v[10:11], v[46:47], s[72:73], v[10:11] op_sel_hi:[0,1,1]
	v_pk_fma_f32 v[8:9], v[46:47], s[68:69], v[8:9] op_sel_hi:[0,1,1]
	v_pk_fma_f32 v[4:5], v[46:47], s[78:79], v[4:5] op_sel_hi:[0,1,1]
	v_fmac_f32_e32 v34, vcc_hi, v18
	v_pk_fma_f32 v[12:13], v[18:19], s[82:83], v[12:13] op_sel_hi:[0,1,1]
	v_pk_fma_f32 v[10:11], v[18:19], s[80:81], v[10:11] op_sel_hi:[0,1,1]
	v_pk_fma_f32 v[8:9], v[18:19], s[76:77], v[8:9] op_sel_hi:[0,1,1]
	v_pk_fma_f32 v[4:5], v[18:19], s[86:87], v[4:5] op_sel_hi:[0,1,1]
	v_lshl_add_u64 v[6:7], v[6:7], 0, s[40:41]
	v_fmac_f32_e32 v34, s4, v16
	v_pk_fma_f32 v[12:13], v[16:17], s[90:91], v[12:13] op_sel_hi:[0,1,1]
	v_pk_fma_f32 v[10:11], v[16:17], s[88:89], v[10:11] op_sel_hi:[0,1,1]
	v_pk_fma_f32 v[8:9], v[16:17], s[84:85], v[8:9] op_sel_hi:[0,1,1]
	v_pk_fma_f32 v[4:5], v[16:17], s[92:93], v[4:5] op_sel_hi:[0,1,1]
	s_mov_b32 s6, 0xfffdc000
	v_add_co_u32_e64 v38, s[6:7], s6, v6
	v_add_co_u32_e32 v14, vcc, 0xfffd6000, v6
	s_nop 0
	v_addc_co_u32_e64 v39, s[6:7], -1, v7, s[6:7]
	s_mov_b32 s6, 0xfffe2000
	s_nop 0
	v_add_co_u32_e64 v40, s[6:7], s6, v6
	s_waitcnt vmcnt(32)
	v_mov_b32_e32 v16, v91
	s_nop 0
	v_addc_co_u32_e64 v41, s[6:7], -1, v7, s[6:7]
	s_mov_b32 s6, 0xfffe8000
	s_nop 0
	v_add_co_u32_e64 v42, s[6:7], s6, v6
	v_addc_co_u32_e32 v15, vcc, -1, v7, vcc
	s_nop 0
	v_addc_co_u32_e64 v43, s[6:7], -1, v7, s[6:7]
	s_mov_b32 s6, 0xfffee000
	s_nop 0
	v_add_co_u32_e64 v44, s[6:7], s6, v6
	v_readlane_b32 s9, v27, s96
	s_nop 0
	v_addc_co_u32_e64 v45, s[6:7], -1, v7, s[6:7]
	s_mov_b32 s6, 0xffff4000
	s_nop 0
	v_add_co_u32_e64 v46, s[6:7], s6, v6
	v_readlane_b32 s11, v28, s96
	s_nop 0
	v_addc_co_u32_e64 v47, s[6:7], -1, v7, s[6:7]
	s_movk_i32 s6, 0xa000
	s_nop 0
	v_add_co_u32_e64 v48, s[6:7], s6, v6
	v_readlane_b32 s26, v29, s96
	s_nop 0
	v_addc_co_u32_e64 v49, s[6:7], -1, v7, s[6:7]
	v_mov_b32_e32 v38, v85
	s_nop 0
	v_mov_b32_e32 v40, v86
	s_nop 0
	v_mov_b32_e32 v42, v87
	s_nop 0
	v_mov_b32_e32 v44, v88
	s_nop 0
	v_mov_b32_e32 v46, v89
	s_nop 0
	v_mov_b32_e32 v18, v90
	s_nop 0
	v_mov_b32_e32 v14, v84
	v_readlane_b32 s97, v30, s96
	v_readlane_b32 s27, v31, s96
	v_readlane_b32 s10, v32, s96
	v_readlane_b32 s8, v33, s96
	v_readlane_b32 s29, v35, s96
	v_readlane_b32 s28, v36, s96
	s_add_i32 s36, s96, 1
	s_add_i32 s52, s96, 2
	v_readlane_b32 s7, v27, s36
	v_readlane_b32 s31, v28, s36
	v_readlane_b32 s34, v29, s36
	v_readlane_b32 s94, v30, s36
	v_readlane_b32 s35, v31, s36
	v_readlane_b32 s30, v32, s36
	v_readlane_b32 s6, v33, s36
	v_readlane_b32 s47, v35, s36
	v_readlane_b32 s46, v36, s36
	s_add_i32 s33, s96, 3
	v_readlane_b32 s37, v27, s52
	v_readlane_b32 s49, v28, s52
	v_readlane_b32 s50, v29, s52
	v_readlane_b32 s44, v30, s52
	v_readlane_b32 s51, v31, s52
	v_readlane_b32 s48, v32, s52
	v_readlane_b32 s36, v33, s52
	v_readlane_b32 s53, v35, s52
	v_readlane_b32 s52, v36, s52
	s_add_i32 s68, s96, 4
	v_readlane_b32 s55, v27, s33
	v_readlane_b32 s57, v28, s33
	v_readlane_b32 s58, v29, s33
	v_readlane_b32 s45, v30, s33
	v_readlane_b32 s59, v31, s33
	v_readlane_b32 s56, v32, s33
	v_readlane_b32 s54, v33, s33
	v_readlane_b32 s63, v35, s33
	v_readlane_b32 s62, v36, s33
	s_add_i32 s4, s96, 5
	v_readlane_b32 s61, v27, s68
	v_readlane_b32 s65, v28, s68
	v_readlane_b32 s66, v29, s68
	v_readlane_b32 s33, v30, s68
	v_readlane_b32 s67, v31, s68
	v_readlane_b32 s64, v32, s68
	v_readlane_b32 s60, v33, s68
	v_readlane_b32 s71, v35, s68
	v_readlane_b32 s70, v36, s68
	s_add_i32 s5, s96, 6
	v_readlane_b32 s69, v27, s4
	v_readlane_b32 s73, v28, s4
	v_readlane_b32 s74, v29, s4
	v_readlane_b32 vcc_lo, v30, s4
	v_readlane_b32 s75, v31, s4
	v_readlane_b32 s72, v32, s4
	v_readlane_b32 s68, v33, s4
	v_readlane_b32 s79, v35, s4
	v_readlane_b32 s78, v36, s4
	s_add_i32 s40, s96, 7
	v_readlane_b32 s77, v27, s5
	v_readlane_b32 s81, v28, s5
	v_readlane_b32 s82, v29, s5
	v_readlane_b32 vcc_hi, v30, s5
	v_readlane_b32 s83, v31, s5
	v_readlane_b32 s80, v32, s5
	v_readlane_b32 s76, v33, s5
	v_readlane_b32 s87, v35, s5
	v_readlane_b32 s86, v36, s5
	s_add_i32 s96, s96, 8
	v_readlane_b32 s85, v27, s40
	v_readlane_b32 s89, v28, s40
	v_readlane_b32 s90, v29, s40
	v_readlane_b32 s91, v31, s40
	v_readlane_b32 s88, v32, s40
	v_readlane_b32 s84, v33, s40
	v_readlane_b32 s93, v35, s40
	v_readlane_b32 s92, v36, s40
	v_readlane_b32 s4, v30, s40
	s_mov_b64 s[40:41], 0x30000
	s_cmp_eq_u32 s96, 64
	s_nop 0
	v_fmac_f32_e32 v34, s97, v14
	v_pk_fma_f32 v[12:13], v[14:15], s[26:27], v[12:13] op_sel_hi:[0,1,1]
	v_pk_fma_f32 v[10:11], v[14:15], s[10:11], v[10:11] op_sel_hi:[0,1,1]
	v_pk_fma_f32 v[8:9], v[14:15], s[8:9], v[8:9] op_sel_hi:[0,1,1]
	v_pk_fma_f32 v[4:5], v[14:15], s[28:29], v[4:5] op_sel_hi:[0,1,1]
	v_fmac_f32_e32 v34, s94, v38
	v_pk_fma_f32 v[12:13], v[38:39], s[34:35], v[12:13] op_sel_hi:[0,1,1]
	v_pk_fma_f32 v[10:11], v[38:39], s[30:31], v[10:11] op_sel_hi:[0,1,1]
	v_pk_fma_f32 v[8:9], v[38:39], s[6:7], v[8:9] op_sel_hi:[0,1,1]
	v_pk_fma_f32 v[4:5], v[38:39], s[46:47], v[4:5] op_sel_hi:[0,1,1]
	v_fmac_f32_e32 v34, s44, v40
	v_pk_fma_f32 v[12:13], v[40:41], s[50:51], v[12:13] op_sel_hi:[0,1,1]
	v_pk_fma_f32 v[10:11], v[40:41], s[48:49], v[10:11] op_sel_hi:[0,1,1]
	v_pk_fma_f32 v[8:9], v[40:41], s[36:37], v[8:9] op_sel_hi:[0,1,1]
	v_pk_fma_f32 v[4:5], v[40:41], s[52:53], v[4:5] op_sel_hi:[0,1,1]
	v_fmac_f32_e32 v34, s45, v42
	v_pk_fma_f32 v[12:13], v[42:43], s[58:59], v[12:13] op_sel_hi:[0,1,1]
	v_pk_fma_f32 v[10:11], v[42:43], s[56:57], v[10:11] op_sel_hi:[0,1,1]
	v_pk_fma_f32 v[8:9], v[42:43], s[54:55], v[8:9] op_sel_hi:[0,1,1]
	v_pk_fma_f32 v[4:5], v[42:43], s[62:63], v[4:5] op_sel_hi:[0,1,1]
	v_fmac_f32_e32 v34, s33, v44
	v_pk_fma_f32 v[12:13], v[44:45], s[66:67], v[12:13] op_sel_hi:[0,1,1]
	v_pk_fma_f32 v[10:11], v[44:45], s[64:65], v[10:11] op_sel_hi:[0,1,1]
	v_pk_fma_f32 v[8:9], v[44:45], s[60:61], v[8:9] op_sel_hi:[0,1,1]
	v_pk_fma_f32 v[4:5], v[44:45], s[70:71], v[4:5] op_sel_hi:[0,1,1]
	v_fmac_f32_e32 v34, vcc_lo, v46
	v_pk_fma_f32 v[12:13], v[46:47], s[74:75], v[12:13] op_sel_hi:[0,1,1]
	v_pk_fma_f32 v[10:11], v[46:47], s[72:73], v[10:11] op_sel_hi:[0,1,1]
	v_pk_fma_f32 v[8:9], v[46:47], s[68:69], v[8:9] op_sel_hi:[0,1,1]
	v_pk_fma_f32 v[4:5], v[46:47], s[78:79], v[4:5] op_sel_hi:[0,1,1]
	v_fmac_f32_e32 v34, vcc_hi, v18
	v_pk_fma_f32 v[12:13], v[18:19], s[82:83], v[12:13] op_sel_hi:[0,1,1]
	v_pk_fma_f32 v[10:11], v[18:19], s[80:81], v[10:11] op_sel_hi:[0,1,1]
	v_pk_fma_f32 v[8:9], v[18:19], s[76:77], v[8:9] op_sel_hi:[0,1,1]
	v_pk_fma_f32 v[4:5], v[18:19], s[86:87], v[4:5] op_sel_hi:[0,1,1]
	v_lshl_add_u64 v[6:7], v[6:7], 0, s[40:41]
	v_fmac_f32_e32 v34, s4, v16
	v_pk_fma_f32 v[12:13], v[16:17], s[90:91], v[12:13] op_sel_hi:[0,1,1]
	v_pk_fma_f32 v[10:11], v[16:17], s[88:89], v[10:11] op_sel_hi:[0,1,1]
	v_pk_fma_f32 v[8:9], v[16:17], s[84:85], v[8:9] op_sel_hi:[0,1,1]
	v_pk_fma_f32 v[4:5], v[16:17], s[92:93], v[4:5] op_sel_hi:[0,1,1]
	s_mov_b32 s6, 0xfffdc000
	v_add_co_u32_e64 v38, s[6:7], s6, v6
	v_add_co_u32_e32 v14, vcc, 0xfffd6000, v6
	s_nop 0
	v_addc_co_u32_e64 v39, s[6:7], -1, v7, s[6:7]
	s_mov_b32 s6, 0xfffe2000
	s_nop 0
	v_add_co_u32_e64 v40, s[6:7], s6, v6
	s_waitcnt vmcnt(24)
	v_mov_b32_e32 v16, v99
	s_nop 0
	v_addc_co_u32_e64 v41, s[6:7], -1, v7, s[6:7]
	s_mov_b32 s6, 0xfffe8000
	s_nop 0
	v_add_co_u32_e64 v42, s[6:7], s6, v6
	v_addc_co_u32_e32 v15, vcc, -1, v7, vcc
	s_nop 0
	v_addc_co_u32_e64 v43, s[6:7], -1, v7, s[6:7]
	s_mov_b32 s6, 0xfffee000
	s_nop 0
	v_add_co_u32_e64 v44, s[6:7], s6, v6
	v_readlane_b32 s9, v27, s96
	s_nop 0
	v_addc_co_u32_e64 v45, s[6:7], -1, v7, s[6:7]
	s_mov_b32 s6, 0xffff4000
	s_nop 0
	v_add_co_u32_e64 v46, s[6:7], s6, v6
	v_readlane_b32 s11, v28, s96
	s_nop 0
	v_addc_co_u32_e64 v47, s[6:7], -1, v7, s[6:7]
	s_movk_i32 s6, 0xa000
	s_nop 0
	v_add_co_u32_e64 v48, s[6:7], s6, v6
	v_readlane_b32 s26, v29, s96
	s_nop 0
	v_addc_co_u32_e64 v49, s[6:7], -1, v7, s[6:7]
	v_mov_b32_e32 v38, v93
	s_nop 0
	v_mov_b32_e32 v40, v94
	s_nop 0
	v_mov_b32_e32 v42, v95
	s_nop 0
	v_mov_b32_e32 v44, v96
	s_nop 0
	v_mov_b32_e32 v46, v97
	s_nop 0
	v_mov_b32_e32 v18, v98
	s_nop 0
	v_mov_b32_e32 v14, v92
	v_readlane_b32 s97, v30, s96
	v_readlane_b32 s27, v31, s96
	v_readlane_b32 s10, v32, s96
	v_readlane_b32 s8, v33, s96
	v_readlane_b32 s29, v35, s96
	v_readlane_b32 s28, v36, s96
	s_add_i32 s36, s96, 1
	s_add_i32 s52, s96, 2
	v_readlane_b32 s7, v27, s36
	v_readlane_b32 s31, v28, s36
	v_readlane_b32 s34, v29, s36
	v_readlane_b32 s94, v30, s36
	v_readlane_b32 s35, v31, s36
	v_readlane_b32 s30, v32, s36
	v_readlane_b32 s6, v33, s36
	v_readlane_b32 s47, v35, s36
	v_readlane_b32 s46, v36, s36
	s_add_i32 s33, s96, 3
	v_readlane_b32 s37, v27, s52
	v_readlane_b32 s49, v28, s52
	v_readlane_b32 s50, v29, s52
	v_readlane_b32 s44, v30, s52
	v_readlane_b32 s51, v31, s52
	v_readlane_b32 s48, v32, s52
	v_readlane_b32 s36, v33, s52
	v_readlane_b32 s53, v35, s52
	v_readlane_b32 s52, v36, s52
	s_add_i32 s68, s96, 4
	v_readlane_b32 s55, v27, s33
	v_readlane_b32 s57, v28, s33
	v_readlane_b32 s58, v29, s33
	v_readlane_b32 s45, v30, s33
	v_readlane_b32 s59, v31, s33
	v_readlane_b32 s56, v32, s33
	v_readlane_b32 s54, v33, s33
	v_readlane_b32 s63, v35, s33
	v_readlane_b32 s62, v36, s33
	s_add_i32 s4, s96, 5
	v_readlane_b32 s61, v27, s68
	v_readlane_b32 s65, v28, s68
	v_readlane_b32 s66, v29, s68
	v_readlane_b32 s33, v30, s68
	v_readlane_b32 s67, v31, s68
	v_readlane_b32 s64, v32, s68
	v_readlane_b32 s60, v33, s68
	v_readlane_b32 s71, v35, s68
	v_readlane_b32 s70, v36, s68
	s_add_i32 s5, s96, 6
	v_readlane_b32 s69, v27, s4
	v_readlane_b32 s73, v28, s4
	v_readlane_b32 s74, v29, s4
	v_readlane_b32 vcc_lo, v30, s4
	v_readlane_b32 s75, v31, s4
	v_readlane_b32 s72, v32, s4
	v_readlane_b32 s68, v33, s4
	v_readlane_b32 s79, v35, s4
	v_readlane_b32 s78, v36, s4
	s_add_i32 s40, s96, 7
	v_readlane_b32 s77, v27, s5
	v_readlane_b32 s81, v28, s5
	v_readlane_b32 s82, v29, s5
	v_readlane_b32 vcc_hi, v30, s5
	v_readlane_b32 s83, v31, s5
	v_readlane_b32 s80, v32, s5
	v_readlane_b32 s76, v33, s5
	v_readlane_b32 s87, v35, s5
	v_readlane_b32 s86, v36, s5
	s_add_i32 s96, s96, 8
	v_readlane_b32 s85, v27, s40
	v_readlane_b32 s89, v28, s40
	v_readlane_b32 s90, v29, s40
	v_readlane_b32 s91, v31, s40
	v_readlane_b32 s88, v32, s40
	v_readlane_b32 s84, v33, s40
	v_readlane_b32 s93, v35, s40
	v_readlane_b32 s92, v36, s40
	v_readlane_b32 s4, v30, s40
	s_mov_b64 s[40:41], 0x30000
	s_cmp_eq_u32 s96, 64
	s_nop 0
	v_fmac_f32_e32 v34, s97, v14
	v_pk_fma_f32 v[12:13], v[14:15], s[26:27], v[12:13] op_sel_hi:[0,1,1]
	v_pk_fma_f32 v[10:11], v[14:15], s[10:11], v[10:11] op_sel_hi:[0,1,1]
	v_pk_fma_f32 v[8:9], v[14:15], s[8:9], v[8:9] op_sel_hi:[0,1,1]
	v_pk_fma_f32 v[4:5], v[14:15], s[28:29], v[4:5] op_sel_hi:[0,1,1]
	v_fmac_f32_e32 v34, s94, v38
	v_pk_fma_f32 v[12:13], v[38:39], s[34:35], v[12:13] op_sel_hi:[0,1,1]
	v_pk_fma_f32 v[10:11], v[38:39], s[30:31], v[10:11] op_sel_hi:[0,1,1]
	v_pk_fma_f32 v[8:9], v[38:39], s[6:7], v[8:9] op_sel_hi:[0,1,1]
	v_pk_fma_f32 v[4:5], v[38:39], s[46:47], v[4:5] op_sel_hi:[0,1,1]
	v_fmac_f32_e32 v34, s44, v40
	v_pk_fma_f32 v[12:13], v[40:41], s[50:51], v[12:13] op_sel_hi:[0,1,1]
	v_pk_fma_f32 v[10:11], v[40:41], s[48:49], v[10:11] op_sel_hi:[0,1,1]
	v_pk_fma_f32 v[8:9], v[40:41], s[36:37], v[8:9] op_sel_hi:[0,1,1]
	v_pk_fma_f32 v[4:5], v[40:41], s[52:53], v[4:5] op_sel_hi:[0,1,1]
	v_fmac_f32_e32 v34, s45, v42
	v_pk_fma_f32 v[12:13], v[42:43], s[58:59], v[12:13] op_sel_hi:[0,1,1]
	v_pk_fma_f32 v[10:11], v[42:43], s[56:57], v[10:11] op_sel_hi:[0,1,1]
	v_pk_fma_f32 v[8:9], v[42:43], s[54:55], v[8:9] op_sel_hi:[0,1,1]
	v_pk_fma_f32 v[4:5], v[42:43], s[62:63], v[4:5] op_sel_hi:[0,1,1]
	v_fmac_f32_e32 v34, s33, v44
	v_pk_fma_f32 v[12:13], v[44:45], s[66:67], v[12:13] op_sel_hi:[0,1,1]
	v_pk_fma_f32 v[10:11], v[44:45], s[64:65], v[10:11] op_sel_hi:[0,1,1]
	v_pk_fma_f32 v[8:9], v[44:45], s[60:61], v[8:9] op_sel_hi:[0,1,1]
	v_pk_fma_f32 v[4:5], v[44:45], s[70:71], v[4:5] op_sel_hi:[0,1,1]
	v_fmac_f32_e32 v34, vcc_lo, v46
	v_pk_fma_f32 v[12:13], v[46:47], s[74:75], v[12:13] op_sel_hi:[0,1,1]
	v_pk_fma_f32 v[10:11], v[46:47], s[72:73], v[10:11] op_sel_hi:[0,1,1]
	v_pk_fma_f32 v[8:9], v[46:47], s[68:69], v[8:9] op_sel_hi:[0,1,1]
	v_pk_fma_f32 v[4:5], v[46:47], s[78:79], v[4:5] op_sel_hi:[0,1,1]
	v_fmac_f32_e32 v34, vcc_hi, v18
	v_pk_fma_f32 v[12:13], v[18:19], s[82:83], v[12:13] op_sel_hi:[0,1,1]
	v_pk_fma_f32 v[10:11], v[18:19], s[80:81], v[10:11] op_sel_hi:[0,1,1]
	v_pk_fma_f32 v[8:9], v[18:19], s[76:77], v[8:9] op_sel_hi:[0,1,1]
	v_pk_fma_f32 v[4:5], v[18:19], s[86:87], v[4:5] op_sel_hi:[0,1,1]
	v_lshl_add_u64 v[6:7], v[6:7], 0, s[40:41]
	v_fmac_f32_e32 v34, s4, v16
	v_pk_fma_f32 v[12:13], v[16:17], s[90:91], v[12:13] op_sel_hi:[0,1,1]
	v_pk_fma_f32 v[10:11], v[16:17], s[88:89], v[10:11] op_sel_hi:[0,1,1]
	v_pk_fma_f32 v[8:9], v[16:17], s[84:85], v[8:9] op_sel_hi:[0,1,1]
	v_pk_fma_f32 v[4:5], v[16:17], s[92:93], v[4:5] op_sel_hi:[0,1,1]
	s_mov_b32 s6, 0xfffdc000
	v_add_co_u32_e64 v38, s[6:7], s6, v6
	v_add_co_u32_e32 v14, vcc, 0xfffd6000, v6
	s_nop 0
	v_addc_co_u32_e64 v39, s[6:7], -1, v7, s[6:7]
	s_mov_b32 s6, 0xfffe2000
	s_nop 0
	v_add_co_u32_e64 v40, s[6:7], s6, v6
	s_waitcnt vmcnt(16)
	v_mov_b32_e32 v16, v107
	s_nop 0
	v_addc_co_u32_e64 v41, s[6:7], -1, v7, s[6:7]
	s_mov_b32 s6, 0xfffe8000
	s_nop 0
	v_add_co_u32_e64 v42, s[6:7], s6, v6
	v_addc_co_u32_e32 v15, vcc, -1, v7, vcc
	s_nop 0
	v_addc_co_u32_e64 v43, s[6:7], -1, v7, s[6:7]
	s_mov_b32 s6, 0xfffee000
	s_nop 0
	v_add_co_u32_e64 v44, s[6:7], s6, v6
	v_readlane_b32 s9, v27, s96
	s_nop 0
	v_addc_co_u32_e64 v45, s[6:7], -1, v7, s[6:7]
	s_mov_b32 s6, 0xffff4000
	s_nop 0
	v_add_co_u32_e64 v46, s[6:7], s6, v6
	v_readlane_b32 s11, v28, s96
	s_nop 0
	v_addc_co_u32_e64 v47, s[6:7], -1, v7, s[6:7]
	s_movk_i32 s6, 0xa000
	s_nop 0
	v_add_co_u32_e64 v48, s[6:7], s6, v6
	v_readlane_b32 s26, v29, s96
	s_nop 0
	v_addc_co_u32_e64 v49, s[6:7], -1, v7, s[6:7]
	v_mov_b32_e32 v38, v101
	s_nop 0
	v_mov_b32_e32 v40, v102
	s_nop 0
	v_mov_b32_e32 v42, v103
	s_nop 0
	v_mov_b32_e32 v44, v104
	s_nop 0
	v_mov_b32_e32 v46, v105
	s_nop 0
	v_mov_b32_e32 v18, v106
	s_nop 0
	v_mov_b32_e32 v14, v100
	v_readlane_b32 s97, v30, s96
	v_readlane_b32 s27, v31, s96
	v_readlane_b32 s10, v32, s96
	v_readlane_b32 s8, v33, s96
	v_readlane_b32 s29, v35, s96
	v_readlane_b32 s28, v36, s96
	s_add_i32 s36, s96, 1
	s_add_i32 s52, s96, 2
	v_readlane_b32 s7, v27, s36
	v_readlane_b32 s31, v28, s36
	v_readlane_b32 s34, v29, s36
	v_readlane_b32 s94, v30, s36
	v_readlane_b32 s35, v31, s36
	v_readlane_b32 s30, v32, s36
	v_readlane_b32 s6, v33, s36
	v_readlane_b32 s47, v35, s36
	v_readlane_b32 s46, v36, s36
	s_add_i32 s33, s96, 3
	v_readlane_b32 s37, v27, s52
	v_readlane_b32 s49, v28, s52
	v_readlane_b32 s50, v29, s52
	v_readlane_b32 s44, v30, s52
	v_readlane_b32 s51, v31, s52
	v_readlane_b32 s48, v32, s52
	v_readlane_b32 s36, v33, s52
	v_readlane_b32 s53, v35, s52
	v_readlane_b32 s52, v36, s52
	s_add_i32 s68, s96, 4
	v_readlane_b32 s55, v27, s33
	v_readlane_b32 s57, v28, s33
	v_readlane_b32 s58, v29, s33
	v_readlane_b32 s45, v30, s33
	v_readlane_b32 s59, v31, s33
	v_readlane_b32 s56, v32, s33
	v_readlane_b32 s54, v33, s33
	v_readlane_b32 s63, v35, s33
	v_readlane_b32 s62, v36, s33
	s_add_i32 s4, s96, 5
	v_readlane_b32 s61, v27, s68
	v_readlane_b32 s65, v28, s68
	v_readlane_b32 s66, v29, s68
	v_readlane_b32 s33, v30, s68
	v_readlane_b32 s67, v31, s68
	v_readlane_b32 s64, v32, s68
	v_readlane_b32 s60, v33, s68
	v_readlane_b32 s71, v35, s68
	v_readlane_b32 s70, v36, s68
	s_add_i32 s5, s96, 6
	v_readlane_b32 s69, v27, s4
	v_readlane_b32 s73, v28, s4
	v_readlane_b32 s74, v29, s4
	v_readlane_b32 vcc_lo, v30, s4
	v_readlane_b32 s75, v31, s4
	v_readlane_b32 s72, v32, s4
	v_readlane_b32 s68, v33, s4
	v_readlane_b32 s79, v35, s4
	v_readlane_b32 s78, v36, s4
	s_add_i32 s40, s96, 7
	v_readlane_b32 s77, v27, s5
	v_readlane_b32 s81, v28, s5
	v_readlane_b32 s82, v29, s5
	v_readlane_b32 vcc_hi, v30, s5
	v_readlane_b32 s83, v31, s5
	v_readlane_b32 s80, v32, s5
	v_readlane_b32 s76, v33, s5
	v_readlane_b32 s87, v35, s5
	v_readlane_b32 s86, v36, s5
	s_add_i32 s96, s96, 8
	v_readlane_b32 s85, v27, s40
	v_readlane_b32 s89, v28, s40
	v_readlane_b32 s90, v29, s40
	v_readlane_b32 s91, v31, s40
	v_readlane_b32 s88, v32, s40
	v_readlane_b32 s84, v33, s40
	v_readlane_b32 s93, v35, s40
	v_readlane_b32 s92, v36, s40
	v_readlane_b32 s4, v30, s40
	s_mov_b64 s[40:41], 0x30000
	s_cmp_eq_u32 s96, 64
	s_nop 0
	v_fmac_f32_e32 v34, s97, v14
	v_pk_fma_f32 v[12:13], v[14:15], s[26:27], v[12:13] op_sel_hi:[0,1,1]
	v_pk_fma_f32 v[10:11], v[14:15], s[10:11], v[10:11] op_sel_hi:[0,1,1]
	v_pk_fma_f32 v[8:9], v[14:15], s[8:9], v[8:9] op_sel_hi:[0,1,1]
	v_pk_fma_f32 v[4:5], v[14:15], s[28:29], v[4:5] op_sel_hi:[0,1,1]
	v_fmac_f32_e32 v34, s94, v38
	v_pk_fma_f32 v[12:13], v[38:39], s[34:35], v[12:13] op_sel_hi:[0,1,1]
	v_pk_fma_f32 v[10:11], v[38:39], s[30:31], v[10:11] op_sel_hi:[0,1,1]
	v_pk_fma_f32 v[8:9], v[38:39], s[6:7], v[8:9] op_sel_hi:[0,1,1]
	v_pk_fma_f32 v[4:5], v[38:39], s[46:47], v[4:5] op_sel_hi:[0,1,1]
	v_fmac_f32_e32 v34, s44, v40
	v_pk_fma_f32 v[12:13], v[40:41], s[50:51], v[12:13] op_sel_hi:[0,1,1]
	v_pk_fma_f32 v[10:11], v[40:41], s[48:49], v[10:11] op_sel_hi:[0,1,1]
	v_pk_fma_f32 v[8:9], v[40:41], s[36:37], v[8:9] op_sel_hi:[0,1,1]
	v_pk_fma_f32 v[4:5], v[40:41], s[52:53], v[4:5] op_sel_hi:[0,1,1]
	v_fmac_f32_e32 v34, s45, v42
	v_pk_fma_f32 v[12:13], v[42:43], s[58:59], v[12:13] op_sel_hi:[0,1,1]
	v_pk_fma_f32 v[10:11], v[42:43], s[56:57], v[10:11] op_sel_hi:[0,1,1]
	v_pk_fma_f32 v[8:9], v[42:43], s[54:55], v[8:9] op_sel_hi:[0,1,1]
	v_pk_fma_f32 v[4:5], v[42:43], s[62:63], v[4:5] op_sel_hi:[0,1,1]
	v_fmac_f32_e32 v34, s33, v44
	v_pk_fma_f32 v[12:13], v[44:45], s[66:67], v[12:13] op_sel_hi:[0,1,1]
	v_pk_fma_f32 v[10:11], v[44:45], s[64:65], v[10:11] op_sel_hi:[0,1,1]
	v_pk_fma_f32 v[8:9], v[44:45], s[60:61], v[8:9] op_sel_hi:[0,1,1]
	v_pk_fma_f32 v[4:5], v[44:45], s[70:71], v[4:5] op_sel_hi:[0,1,1]
	v_fmac_f32_e32 v34, vcc_lo, v46
	v_pk_fma_f32 v[12:13], v[46:47], s[74:75], v[12:13] op_sel_hi:[0,1,1]
	v_pk_fma_f32 v[10:11], v[46:47], s[72:73], v[10:11] op_sel_hi:[0,1,1]
	v_pk_fma_f32 v[8:9], v[46:47], s[68:69], v[8:9] op_sel_hi:[0,1,1]
	v_pk_fma_f32 v[4:5], v[46:47], s[78:79], v[4:5] op_sel_hi:[0,1,1]
	v_fmac_f32_e32 v34, vcc_hi, v18
	v_pk_fma_f32 v[12:13], v[18:19], s[82:83], v[12:13] op_sel_hi:[0,1,1]
	v_pk_fma_f32 v[10:11], v[18:19], s[80:81], v[10:11] op_sel_hi:[0,1,1]
	v_pk_fma_f32 v[8:9], v[18:19], s[76:77], v[8:9] op_sel_hi:[0,1,1]
	v_pk_fma_f32 v[4:5], v[18:19], s[86:87], v[4:5] op_sel_hi:[0,1,1]
	v_lshl_add_u64 v[6:7], v[6:7], 0, s[40:41]
	v_fmac_f32_e32 v34, s4, v16
	v_pk_fma_f32 v[12:13], v[16:17], s[90:91], v[12:13] op_sel_hi:[0,1,1]
	v_pk_fma_f32 v[10:11], v[16:17], s[88:89], v[10:11] op_sel_hi:[0,1,1]
	v_pk_fma_f32 v[8:9], v[16:17], s[84:85], v[8:9] op_sel_hi:[0,1,1]
	v_pk_fma_f32 v[4:5], v[16:17], s[92:93], v[4:5] op_sel_hi:[0,1,1]
	s_mov_b32 s6, 0xfffdc000
	v_add_co_u32_e64 v38, s[6:7], s6, v6
	v_add_co_u32_e32 v14, vcc, 0xfffd6000, v6
	s_nop 0
	v_addc_co_u32_e64 v39, s[6:7], -1, v7, s[6:7]
	s_mov_b32 s6, 0xfffe2000
	s_nop 0
	v_add_co_u32_e64 v40, s[6:7], s6, v6
	s_waitcnt vmcnt(8)
	v_mov_b32_e32 v16, v115
	s_nop 0
	v_addc_co_u32_e64 v41, s[6:7], -1, v7, s[6:7]
	s_mov_b32 s6, 0xfffe8000
	s_nop 0
	v_add_co_u32_e64 v42, s[6:7], s6, v6
	v_addc_co_u32_e32 v15, vcc, -1, v7, vcc
	s_nop 0
	v_addc_co_u32_e64 v43, s[6:7], -1, v7, s[6:7]
	s_mov_b32 s6, 0xfffee000
	s_nop 0
	v_add_co_u32_e64 v44, s[6:7], s6, v6
	v_readlane_b32 s9, v27, s96
	s_nop 0
	v_addc_co_u32_e64 v45, s[6:7], -1, v7, s[6:7]
	s_mov_b32 s6, 0xffff4000
	s_nop 0
	v_add_co_u32_e64 v46, s[6:7], s6, v6
	v_readlane_b32 s11, v28, s96
	s_nop 0
	v_addc_co_u32_e64 v47, s[6:7], -1, v7, s[6:7]
	s_movk_i32 s6, 0xa000
	s_nop 0
	v_add_co_u32_e64 v48, s[6:7], s6, v6
	v_readlane_b32 s26, v29, s96
	s_nop 0
	v_addc_co_u32_e64 v49, s[6:7], -1, v7, s[6:7]
	v_mov_b32_e32 v38, v109
	s_nop 0
	v_mov_b32_e32 v40, v110
	s_nop 0
	v_mov_b32_e32 v42, v111
	s_nop 0
	v_mov_b32_e32 v44, v112
	s_nop 0
	v_mov_b32_e32 v46, v113
	s_nop 0
	v_mov_b32_e32 v18, v114
	s_nop 0
	v_mov_b32_e32 v14, v108
	v_readlane_b32 s97, v30, s96
	v_readlane_b32 s27, v31, s96
	v_readlane_b32 s10, v32, s96
	v_readlane_b32 s8, v33, s96
	v_readlane_b32 s29, v35, s96
	v_readlane_b32 s28, v36, s96
	s_add_i32 s36, s96, 1
	s_add_i32 s52, s96, 2
	v_readlane_b32 s7, v27, s36
	v_readlane_b32 s31, v28, s36
	v_readlane_b32 s34, v29, s36
	v_readlane_b32 s94, v30, s36
	v_readlane_b32 s35, v31, s36
	v_readlane_b32 s30, v32, s36
	v_readlane_b32 s6, v33, s36
	v_readlane_b32 s47, v35, s36
	v_readlane_b32 s46, v36, s36
	s_add_i32 s33, s96, 3
	v_readlane_b32 s37, v27, s52
	v_readlane_b32 s49, v28, s52
	v_readlane_b32 s50, v29, s52
	v_readlane_b32 s44, v30, s52
	v_readlane_b32 s51, v31, s52
	v_readlane_b32 s48, v32, s52
	v_readlane_b32 s36, v33, s52
	v_readlane_b32 s53, v35, s52
	v_readlane_b32 s52, v36, s52
	s_add_i32 s68, s96, 4
	v_readlane_b32 s55, v27, s33
	v_readlane_b32 s57, v28, s33
	v_readlane_b32 s58, v29, s33
	v_readlane_b32 s45, v30, s33
	v_readlane_b32 s59, v31, s33
	v_readlane_b32 s56, v32, s33
	v_readlane_b32 s54, v33, s33
	v_readlane_b32 s63, v35, s33
	v_readlane_b32 s62, v36, s33
	s_add_i32 s4, s96, 5
	v_readlane_b32 s61, v27, s68
	v_readlane_b32 s65, v28, s68
	v_readlane_b32 s66, v29, s68
	v_readlane_b32 s33, v30, s68
	v_readlane_b32 s67, v31, s68
	v_readlane_b32 s64, v32, s68
	v_readlane_b32 s60, v33, s68
	v_readlane_b32 s71, v35, s68
	v_readlane_b32 s70, v36, s68
	s_add_i32 s5, s96, 6
	v_readlane_b32 s69, v27, s4
	v_readlane_b32 s73, v28, s4
	v_readlane_b32 s74, v29, s4
	v_readlane_b32 vcc_lo, v30, s4
	v_readlane_b32 s75, v31, s4
	v_readlane_b32 s72, v32, s4
	v_readlane_b32 s68, v33, s4
	v_readlane_b32 s79, v35, s4
	v_readlane_b32 s78, v36, s4
	s_add_i32 s40, s96, 7
	v_readlane_b32 s77, v27, s5
	v_readlane_b32 s81, v28, s5
	v_readlane_b32 s82, v29, s5
	v_readlane_b32 vcc_hi, v30, s5
	v_readlane_b32 s83, v31, s5
	v_readlane_b32 s80, v32, s5
	v_readlane_b32 s76, v33, s5
	v_readlane_b32 s87, v35, s5
	v_readlane_b32 s86, v36, s5
	s_add_i32 s96, s96, 8
	v_readlane_b32 s85, v27, s40
	v_readlane_b32 s89, v28, s40
	v_readlane_b32 s90, v29, s40
	v_readlane_b32 s91, v31, s40
	v_readlane_b32 s88, v32, s40
	v_readlane_b32 s84, v33, s40
	v_readlane_b32 s93, v35, s40
	v_readlane_b32 s92, v36, s40
	v_readlane_b32 s4, v30, s40
	s_mov_b64 s[40:41], 0x30000
	s_cmp_eq_u32 s96, 64
	s_nop 0
	v_fmac_f32_e32 v34, s97, v14
	v_pk_fma_f32 v[12:13], v[14:15], s[26:27], v[12:13] op_sel_hi:[0,1,1]
	v_pk_fma_f32 v[10:11], v[14:15], s[10:11], v[10:11] op_sel_hi:[0,1,1]
	v_pk_fma_f32 v[8:9], v[14:15], s[8:9], v[8:9] op_sel_hi:[0,1,1]
	v_pk_fma_f32 v[4:5], v[14:15], s[28:29], v[4:5] op_sel_hi:[0,1,1]
	v_fmac_f32_e32 v34, s94, v38
	v_pk_fma_f32 v[12:13], v[38:39], s[34:35], v[12:13] op_sel_hi:[0,1,1]
	v_pk_fma_f32 v[10:11], v[38:39], s[30:31], v[10:11] op_sel_hi:[0,1,1]
	v_pk_fma_f32 v[8:9], v[38:39], s[6:7], v[8:9] op_sel_hi:[0,1,1]
	v_pk_fma_f32 v[4:5], v[38:39], s[46:47], v[4:5] op_sel_hi:[0,1,1]
	v_fmac_f32_e32 v34, s44, v40
	v_pk_fma_f32 v[12:13], v[40:41], s[50:51], v[12:13] op_sel_hi:[0,1,1]
	v_pk_fma_f32 v[10:11], v[40:41], s[48:49], v[10:11] op_sel_hi:[0,1,1]
	v_pk_fma_f32 v[8:9], v[40:41], s[36:37], v[8:9] op_sel_hi:[0,1,1]
	v_pk_fma_f32 v[4:5], v[40:41], s[52:53], v[4:5] op_sel_hi:[0,1,1]
	v_fmac_f32_e32 v34, s45, v42
	v_pk_fma_f32 v[12:13], v[42:43], s[58:59], v[12:13] op_sel_hi:[0,1,1]
	v_pk_fma_f32 v[10:11], v[42:43], s[56:57], v[10:11] op_sel_hi:[0,1,1]
	v_pk_fma_f32 v[8:9], v[42:43], s[54:55], v[8:9] op_sel_hi:[0,1,1]
	v_pk_fma_f32 v[4:5], v[42:43], s[62:63], v[4:5] op_sel_hi:[0,1,1]
	v_fmac_f32_e32 v34, s33, v44
	v_pk_fma_f32 v[12:13], v[44:45], s[66:67], v[12:13] op_sel_hi:[0,1,1]
	v_pk_fma_f32 v[10:11], v[44:45], s[64:65], v[10:11] op_sel_hi:[0,1,1]
	v_pk_fma_f32 v[8:9], v[44:45], s[60:61], v[8:9] op_sel_hi:[0,1,1]
	v_pk_fma_f32 v[4:5], v[44:45], s[70:71], v[4:5] op_sel_hi:[0,1,1]
	v_fmac_f32_e32 v34, vcc_lo, v46
	v_pk_fma_f32 v[12:13], v[46:47], s[74:75], v[12:13] op_sel_hi:[0,1,1]
	v_pk_fma_f32 v[10:11], v[46:47], s[72:73], v[10:11] op_sel_hi:[0,1,1]
	v_pk_fma_f32 v[8:9], v[46:47], s[68:69], v[8:9] op_sel_hi:[0,1,1]
	v_pk_fma_f32 v[4:5], v[46:47], s[78:79], v[4:5] op_sel_hi:[0,1,1]
	v_fmac_f32_e32 v34, vcc_hi, v18
	v_pk_fma_f32 v[12:13], v[18:19], s[82:83], v[12:13] op_sel_hi:[0,1,1]
	v_pk_fma_f32 v[10:11], v[18:19], s[80:81], v[10:11] op_sel_hi:[0,1,1]
	v_pk_fma_f32 v[8:9], v[18:19], s[76:77], v[8:9] op_sel_hi:[0,1,1]
	v_pk_fma_f32 v[4:5], v[18:19], s[86:87], v[4:5] op_sel_hi:[0,1,1]
	v_lshl_add_u64 v[6:7], v[6:7], 0, s[40:41]
	v_fmac_f32_e32 v34, s4, v16
	v_pk_fma_f32 v[12:13], v[16:17], s[90:91], v[12:13] op_sel_hi:[0,1,1]
	v_pk_fma_f32 v[10:11], v[16:17], s[88:89], v[10:11] op_sel_hi:[0,1,1]
	v_pk_fma_f32 v[8:9], v[16:17], s[84:85], v[8:9] op_sel_hi:[0,1,1]
	v_pk_fma_f32 v[4:5], v[16:17], s[92:93], v[4:5] op_sel_hi:[0,1,1]
	s_mov_b32 s6, 0xfffdc000
	v_add_co_u32_e64 v38, s[6:7], s6, v6
	v_add_co_u32_e32 v14, vcc, 0xfffd6000, v6
	s_nop 0
	v_addc_co_u32_e64 v39, s[6:7], -1, v7, s[6:7]
	s_mov_b32 s6, 0xfffe2000
	s_nop 0
	v_add_co_u32_e64 v40, s[6:7], s6, v6
	s_waitcnt vmcnt(0)
	v_mov_b32_e32 v16, v123
	s_nop 0
	v_addc_co_u32_e64 v41, s[6:7], -1, v7, s[6:7]
	s_mov_b32 s6, 0xfffe8000
	s_nop 0
	v_add_co_u32_e64 v42, s[6:7], s6, v6
	v_addc_co_u32_e32 v15, vcc, -1, v7, vcc
	s_nop 0
	v_addc_co_u32_e64 v43, s[6:7], -1, v7, s[6:7]
	s_mov_b32 s6, 0xfffee000
	s_nop 0
	v_add_co_u32_e64 v44, s[6:7], s6, v6
	v_readlane_b32 s9, v27, s96
	s_nop 0
	v_addc_co_u32_e64 v45, s[6:7], -1, v7, s[6:7]
	s_mov_b32 s6, 0xffff4000
	s_nop 0
	v_add_co_u32_e64 v46, s[6:7], s6, v6
	v_readlane_b32 s11, v28, s96
	s_nop 0
	v_addc_co_u32_e64 v47, s[6:7], -1, v7, s[6:7]
	s_movk_i32 s6, 0xa000
	s_nop 0
	v_add_co_u32_e64 v48, s[6:7], s6, v6
	v_readlane_b32 s26, v29, s96
	s_nop 0
	v_addc_co_u32_e64 v49, s[6:7], -1, v7, s[6:7]
	v_mov_b32_e32 v38, v117
	s_nop 0
	v_mov_b32_e32 v40, v118
	s_nop 0
	v_mov_b32_e32 v42, v119
	s_nop 0
	v_mov_b32_e32 v44, v120
	s_nop 0
	v_mov_b32_e32 v46, v121
	s_nop 0
	v_mov_b32_e32 v18, v122
	s_nop 0
	v_mov_b32_e32 v14, v116
	v_readlane_b32 s97, v30, s96
	v_readlane_b32 s27, v31, s96
	v_readlane_b32 s10, v32, s96
	v_readlane_b32 s8, v33, s96
	v_readlane_b32 s29, v35, s96
	v_readlane_b32 s28, v36, s96
	s_add_i32 s36, s96, 1
	s_add_i32 s52, s96, 2
	v_readlane_b32 s7, v27, s36
	v_readlane_b32 s31, v28, s36
	v_readlane_b32 s34, v29, s36
	v_readlane_b32 s94, v30, s36
	v_readlane_b32 s35, v31, s36
	v_readlane_b32 s30, v32, s36
	v_readlane_b32 s6, v33, s36
	v_readlane_b32 s47, v35, s36
	v_readlane_b32 s46, v36, s36
	s_add_i32 s33, s96, 3
	v_readlane_b32 s37, v27, s52
	v_readlane_b32 s49, v28, s52
	v_readlane_b32 s50, v29, s52
	v_readlane_b32 s44, v30, s52
	v_readlane_b32 s51, v31, s52
	v_readlane_b32 s48, v32, s52
	v_readlane_b32 s36, v33, s52
	v_readlane_b32 s53, v35, s52
	v_readlane_b32 s52, v36, s52
	s_add_i32 s68, s96, 4
	v_readlane_b32 s55, v27, s33
	v_readlane_b32 s57, v28, s33
	v_readlane_b32 s58, v29, s33
	v_readlane_b32 s45, v30, s33
	v_readlane_b32 s59, v31, s33
	v_readlane_b32 s56, v32, s33
	v_readlane_b32 s54, v33, s33
	v_readlane_b32 s63, v35, s33
	v_readlane_b32 s62, v36, s33
	s_add_i32 s4, s96, 5
	v_readlane_b32 s61, v27, s68
	v_readlane_b32 s65, v28, s68
	v_readlane_b32 s66, v29, s68
	v_readlane_b32 s33, v30, s68
	v_readlane_b32 s67, v31, s68
	v_readlane_b32 s64, v32, s68
	v_readlane_b32 s60, v33, s68
	v_readlane_b32 s71, v35, s68
	v_readlane_b32 s70, v36, s68
	s_add_i32 s5, s96, 6
	v_readlane_b32 s69, v27, s4
	v_readlane_b32 s73, v28, s4
	v_readlane_b32 s74, v29, s4
	v_readlane_b32 vcc_lo, v30, s4
	v_readlane_b32 s75, v31, s4
	v_readlane_b32 s72, v32, s4
	v_readlane_b32 s68, v33, s4
	v_readlane_b32 s79, v35, s4
	v_readlane_b32 s78, v36, s4
	s_add_i32 s40, s96, 7
	v_readlane_b32 s77, v27, s5
	v_readlane_b32 s81, v28, s5
	v_readlane_b32 s82, v29, s5
	v_readlane_b32 vcc_hi, v30, s5
	v_readlane_b32 s83, v31, s5
	v_readlane_b32 s80, v32, s5
	v_readlane_b32 s76, v33, s5
	v_readlane_b32 s87, v35, s5
	v_readlane_b32 s86, v36, s5
	s_add_i32 s96, s96, 8
	v_readlane_b32 s85, v27, s40
	v_readlane_b32 s89, v28, s40
	v_readlane_b32 s90, v29, s40
	v_readlane_b32 s91, v31, s40
	v_readlane_b32 s88, v32, s40
	v_readlane_b32 s84, v33, s40
	v_readlane_b32 s93, v35, s40
	v_readlane_b32 s92, v36, s40
	v_readlane_b32 s4, v30, s40
	s_mov_b64 s[40:41], 0x30000
	s_cmp_eq_u32 s96, 64
	s_nop 0
	v_fmac_f32_e32 v34, s97, v14
	v_pk_fma_f32 v[12:13], v[14:15], s[26:27], v[12:13] op_sel_hi:[0,1,1]
	v_pk_fma_f32 v[10:11], v[14:15], s[10:11], v[10:11] op_sel_hi:[0,1,1]
	v_pk_fma_f32 v[8:9], v[14:15], s[8:9], v[8:9] op_sel_hi:[0,1,1]
	v_pk_fma_f32 v[4:5], v[14:15], s[28:29], v[4:5] op_sel_hi:[0,1,1]
	v_fmac_f32_e32 v34, s94, v38
	v_pk_fma_f32 v[12:13], v[38:39], s[34:35], v[12:13] op_sel_hi:[0,1,1]
	v_pk_fma_f32 v[10:11], v[38:39], s[30:31], v[10:11] op_sel_hi:[0,1,1]
	v_pk_fma_f32 v[8:9], v[38:39], s[6:7], v[8:9] op_sel_hi:[0,1,1]
	v_pk_fma_f32 v[4:5], v[38:39], s[46:47], v[4:5] op_sel_hi:[0,1,1]
	v_fmac_f32_e32 v34, s44, v40
	v_pk_fma_f32 v[12:13], v[40:41], s[50:51], v[12:13] op_sel_hi:[0,1,1]
	v_pk_fma_f32 v[10:11], v[40:41], s[48:49], v[10:11] op_sel_hi:[0,1,1]
	v_pk_fma_f32 v[8:9], v[40:41], s[36:37], v[8:9] op_sel_hi:[0,1,1]
	v_pk_fma_f32 v[4:5], v[40:41], s[52:53], v[4:5] op_sel_hi:[0,1,1]
	v_fmac_f32_e32 v34, s45, v42
	v_pk_fma_f32 v[12:13], v[42:43], s[58:59], v[12:13] op_sel_hi:[0,1,1]
	v_pk_fma_f32 v[10:11], v[42:43], s[56:57], v[10:11] op_sel_hi:[0,1,1]
	v_pk_fma_f32 v[8:9], v[42:43], s[54:55], v[8:9] op_sel_hi:[0,1,1]
	v_pk_fma_f32 v[4:5], v[42:43], s[62:63], v[4:5] op_sel_hi:[0,1,1]
	v_fmac_f32_e32 v34, s33, v44
	v_pk_fma_f32 v[12:13], v[44:45], s[66:67], v[12:13] op_sel_hi:[0,1,1]
	v_pk_fma_f32 v[10:11], v[44:45], s[64:65], v[10:11] op_sel_hi:[0,1,1]
	v_pk_fma_f32 v[8:9], v[44:45], s[60:61], v[8:9] op_sel_hi:[0,1,1]
	v_pk_fma_f32 v[4:5], v[44:45], s[70:71], v[4:5] op_sel_hi:[0,1,1]
	v_fmac_f32_e32 v34, vcc_lo, v46
	v_pk_fma_f32 v[12:13], v[46:47], s[74:75], v[12:13] op_sel_hi:[0,1,1]
	v_pk_fma_f32 v[10:11], v[46:47], s[72:73], v[10:11] op_sel_hi:[0,1,1]
	v_pk_fma_f32 v[8:9], v[46:47], s[68:69], v[8:9] op_sel_hi:[0,1,1]
	v_pk_fma_f32 v[4:5], v[46:47], s[78:79], v[4:5] op_sel_hi:[0,1,1]
	v_fmac_f32_e32 v34, vcc_hi, v18
	v_pk_fma_f32 v[12:13], v[18:19], s[82:83], v[12:13] op_sel_hi:[0,1,1]
	v_pk_fma_f32 v[10:11], v[18:19], s[80:81], v[10:11] op_sel_hi:[0,1,1]
	v_pk_fma_f32 v[8:9], v[18:19], s[76:77], v[8:9] op_sel_hi:[0,1,1]
	v_pk_fma_f32 v[4:5], v[18:19], s[86:87], v[4:5] op_sel_hi:[0,1,1]
	v_lshl_add_u64 v[6:7], v[6:7], 0, s[40:41]
	v_fmac_f32_e32 v34, s4, v16
	v_pk_fma_f32 v[12:13], v[16:17], s[90:91], v[12:13] op_sel_hi:[0,1,1]
	v_pk_fma_f32 v[10:11], v[16:17], s[88:89], v[10:11] op_sel_hi:[0,1,1]
	v_pk_fma_f32 v[8:9], v[16:17], s[84:85], v[8:9] op_sel_hi:[0,1,1]
	v_pk_fma_f32 v[4:5], v[16:17], s[92:93], v[4:5] op_sel_hi:[0,1,1]
	v_lshl_add_u32 v14, v26, 3, v26
	v_mov_b64_e32 v[6:7], s[14:15]
	v_mad_i64_i32 v[6:7], s[4:5], v14, s39, v[6:7]
	v_lshl_add_u64 v[2:3], v[2:3], 2, v[6:7]
	v_add_co_u32_e32 v6, vcc, 0x6000, v2
	flat_store_dword v[2:3], v9
	s_nop 0
	v_addc_co_u32_e32 v7, vcc, 0, v3, vcc
	flat_store_dword v[6:7], v11
	v_add_co_u32_e32 v6, vcc, 0xc000, v2
	v_add_u32_e32 v17, s3, v17
	s_nop 0
	v_addc_co_u32_e32 v7, vcc, 0, v3, vcc
	flat_store_dword v[6:7], v12
	v_add_co_u32_e32 v6, vcc, 0x12000, v2
	s_movk_i32 s4, 0x5ff
	s_nop 0
	v_addc_co_u32_e32 v7, vcc, 0, v3, vcc
	flat_store_dword v[6:7], v34
	v_add_co_u32_e32 v6, vcc, 0x18000, v2
	s_nop 1
	v_addc_co_u32_e32 v7, vcc, 0, v3, vcc
	flat_store_dword v[6:7], v13
	v_add_co_u32_e32 v6, vcc, 0x1e000, v2
	s_nop 1
	v_addc_co_u32_e32 v7, vcc, 0, v3, vcc
	flat_store_dword v[6:7], v10
	v_add_co_u32_e32 v6, vcc, 0x24000, v2
	s_nop 1
	v_addc_co_u32_e32 v7, vcc, 0, v3, vcc
	flat_store_dword v[6:7], v8
	v_add_co_u32_e32 v6, vcc, 0x2a000, v2
	s_nop 1
	v_addc_co_u32_e32 v7, vcc, 0, v3, vcc
	v_add_co_u32_e32 v2, vcc, 0x30000, v2
	flat_store_dword v[6:7], v5
	s_nop 0
	v_addc_co_u32_e32 v3, vcc, 0, v3, vcc
	v_cmp_lt_i32_e32 vcc, s4, v17
	s_or_b64 s[24:25], vcc, s[24:25]
	flat_store_dword v[2:3], v4
	s_andn2_b64 exec, exec, s[24:25]
	s_cbranch_execnz .LBB0_39
